# SSD in-proj dt-column epilogue rewritten by hand (bias loaded once, no per-element waits); states-phase Bm staging loads batched; y-phase head barrier after staging loads
# speedup vs baseline: 1.0193x; 1.0110x over previous
.LBB0_1302:
	s_and_b64 vcc, exec, s[0:1]
	s_cbranch_vccz .LBB0_1816
	v_or_b32_e32 v132, v239, v158
	v_add_u32_e32 v135, 0xffffe800, v130
	v_lshlrev_b32_e32 v135, 2, v135
	global_load_dword v138, v135, s[14:15]
	global_load_dword v139, v135, s[14:15] offset:128
	v_lshl_add_u32 v134, v132, 8, v135
	s_mov_b32 s100, 0x3c23d70a
	s_mov_b32 s101, 0xbeaaaaab
	s_waitcnt vmcnt(0)
	s_mov_b64 s[0:1], s[12:13]
	v_add_f32_e32 v112, v112, v138
	v_add_f32_e32 v96, v96, v139
	v_mul_f32_e32 v128, 0xbfb8aa3b, v112
	v_mul_f32_e32 v133, 0xbfb8aa3b, v96
	v_exp_f32_e64 v128, -|v128|
	v_exp_f32_e64 v133, -|v133|
	v_max_f32_e32 v112, 0, v112
	v_max_f32_e32 v96, 0, v96
	v_fma_f32 v131, v128, s101, 0.5
	v_fma_f32 v136, v133, s101, 0.5
	v_cmp_le_f32_e32 vcc, s100, v128
	v_cmp_le_f32_e64 s[24:25], s100, v133
	v_fma_f32 v131, -v128, v131, 1.0
	v_fma_f32 v136, -v133, v136, 1.0
	v_add_f32_e32 v132, 1.0, v128
	v_add_f32_e32 v137, 1.0, v133
	v_mul_f32_e32 v131, v128, v131
	v_mul_f32_e32 v136, v133, v136
	v_log_f32_e32 v132, v132
	v_log_f32_e32 v137, v137
	v_mul_f32_e32 v128, 0xbf317217, v132
	v_mul_f32_e32 v133, 0xbf317217, v137
	v_fmac_f32_e32 v128, 0x3f317217, v132
	v_fmac_f32_e32 v133, 0x3f317217, v137
	v_fmac_f32_e32 v128, 0x3377d1cf, v132
	v_fmac_f32_e32 v133, 0x3377d1cf, v137
	v_fmac_f32_e32 v128, 0x3f317217, v132
	v_fmac_f32_e32 v133, 0x3f317217, v137
	v_cndmask_b32_e32 v131, v131, v128, vcc
	v_cndmask_b32_e64 v136, v136, v133, s[24:25]
	v_add_f32_e32 v112, v112, v131
	v_add_f32_e32 v96, v96, v136
	global_store_dword v134, v112, s[0:1]
	global_store_dword v134, v96, s[0:1] offset:128
	v_add_f32_e32 v113, v113, v138
	v_add_f32_e32 v97, v97, v139
	v_mul_f32_e32 v128, 0xbfb8aa3b, v113
	v_mul_f32_e32 v133, 0xbfb8aa3b, v97
	v_exp_f32_e64 v128, -|v128|
	v_exp_f32_e64 v133, -|v133|
	v_max_f32_e32 v113, 0, v113
	v_max_f32_e32 v97, 0, v97
	v_fma_f32 v131, v128, s101, 0.5
	v_fma_f32 v136, v133, s101, 0.5
	v_cmp_le_f32_e32 vcc, s100, v128
	v_cmp_le_f32_e64 s[24:25], s100, v133
	v_fma_f32 v131, -v128, v131, 1.0
	v_fma_f32 v136, -v133, v136, 1.0
	v_add_f32_e32 v132, 1.0, v128
	v_add_f32_e32 v137, 1.0, v133
	v_mul_f32_e32 v131, v128, v131
	v_mul_f32_e32 v136, v133, v136
	v_log_f32_e32 v132, v132
	v_log_f32_e32 v137, v137
	v_mul_f32_e32 v128, 0xbf317217, v132
	v_mul_f32_e32 v133, 0xbf317217, v137
	v_fmac_f32_e32 v128, 0x3f317217, v132
	v_fmac_f32_e32 v133, 0x3f317217, v137
	v_fmac_f32_e32 v128, 0x3377d1cf, v132
	v_fmac_f32_e32 v133, 0x3377d1cf, v137
	v_fmac_f32_e32 v128, 0x3f317217, v132
	v_fmac_f32_e32 v133, 0x3f317217, v137
	v_cndmask_b32_e32 v131, v131, v128, vcc
	v_cndmask_b32_e64 v136, v136, v133, s[24:25]
	v_add_f32_e32 v113, v113, v131
	v_add_f32_e32 v97, v97, v136
	global_store_dword v134, v113, s[0:1] offset:256
	global_store_dword v134, v97, s[0:1] offset:384
	v_add_f32_e32 v114, v114, v138
	v_add_f32_e32 v98, v98, v139
	v_mul_f32_e32 v128, 0xbfb8aa3b, v114
	v_mul_f32_e32 v133, 0xbfb8aa3b, v98
	v_exp_f32_e64 v128, -|v128|
	v_exp_f32_e64 v133, -|v133|
	v_max_f32_e32 v114, 0, v114
	v_max_f32_e32 v98, 0, v98
	v_fma_f32 v131, v128, s101, 0.5
	v_fma_f32 v136, v133, s101, 0.5
	v_cmp_le_f32_e32 vcc, s100, v128
	v_cmp_le_f32_e64 s[24:25], s100, v133
	v_fma_f32 v131, -v128, v131, 1.0
	v_fma_f32 v136, -v133, v136, 1.0
	v_add_f32_e32 v132, 1.0, v128
	v_add_f32_e32 v137, 1.0, v133
	v_mul_f32_e32 v131, v128, v131
	v_mul_f32_e32 v136, v133, v136
	v_log_f32_e32 v132, v132
	v_log_f32_e32 v137, v137
	v_mul_f32_e32 v128, 0xbf317217, v132
	v_mul_f32_e32 v133, 0xbf317217, v137
	v_fmac_f32_e32 v128, 0x3f317217, v132
	v_fmac_f32_e32 v133, 0x3f317217, v137
	v_fmac_f32_e32 v128, 0x3377d1cf, v132
	v_fmac_f32_e32 v133, 0x3377d1cf, v137
	v_fmac_f32_e32 v128, 0x3f317217, v132
	v_fmac_f32_e32 v133, 0x3f317217, v137
	v_cndmask_b32_e32 v131, v131, v128, vcc
	v_cndmask_b32_e64 v136, v136, v133, s[24:25]
	v_add_f32_e32 v114, v114, v131
	v_add_f32_e32 v98, v98, v136
	global_store_dword v134, v114, s[0:1] offset:512
	global_store_dword v134, v98, s[0:1] offset:640
	v_add_f32_e32 v115, v115, v138
	v_add_f32_e32 v99, v99, v139
	v_mul_f32_e32 v128, 0xbfb8aa3b, v115
	v_mul_f32_e32 v133, 0xbfb8aa3b, v99
	v_exp_f32_e64 v128, -|v128|
	v_exp_f32_e64 v133, -|v133|
	v_max_f32_e32 v115, 0, v115
	v_max_f32_e32 v99, 0, v99
	v_fma_f32 v131, v128, s101, 0.5
	v_fma_f32 v136, v133, s101, 0.5
	v_cmp_le_f32_e32 vcc, s100, v128
	v_cmp_le_f32_e64 s[24:25], s100, v133
	v_fma_f32 v131, -v128, v131, 1.0
	v_fma_f32 v136, -v133, v136, 1.0
	v_add_f32_e32 v132, 1.0, v128
	v_add_f32_e32 v137, 1.0, v133
	v_mul_f32_e32 v131, v128, v131
	v_mul_f32_e32 v136, v133, v136
	v_log_f32_e32 v132, v132
	v_log_f32_e32 v137, v137
	v_mul_f32_e32 v128, 0xbf317217, v132
	v_mul_f32_e32 v133, 0xbf317217, v137
	v_fmac_f32_e32 v128, 0x3f317217, v132
	v_fmac_f32_e32 v133, 0x3f317217, v137
	v_fmac_f32_e32 v128, 0x3377d1cf, v132
	v_fmac_f32_e32 v133, 0x3377d1cf, v137
	v_fmac_f32_e32 v128, 0x3f317217, v132
	v_fmac_f32_e32 v133, 0x3f317217, v137
	v_cndmask_b32_e32 v131, v131, v128, vcc
	v_cndmask_b32_e64 v136, v136, v133, s[24:25]
	v_add_f32_e32 v115, v115, v131
	v_add_f32_e32 v99, v99, v136
	global_store_dword v134, v115, s[0:1] offset:768
	global_store_dword v134, v99, s[0:1] offset:896
	v_add_f32_e32 v116, v116, v138
	v_add_f32_e32 v100, v100, v139
	v_mul_f32_e32 v128, 0xbfb8aa3b, v116
	v_mul_f32_e32 v133, 0xbfb8aa3b, v100
	v_exp_f32_e64 v128, -|v128|
	v_exp_f32_e64 v133, -|v133|
	v_max_f32_e32 v116, 0, v116
	v_max_f32_e32 v100, 0, v100
	v_fma_f32 v131, v128, s101, 0.5
	v_fma_f32 v136, v133, s101, 0.5
	v_cmp_le_f32_e32 vcc, s100, v128
	v_cmp_le_f32_e64 s[24:25], s100, v133
	v_fma_f32 v131, -v128, v131, 1.0
	v_fma_f32 v136, -v133, v136, 1.0
	v_add_f32_e32 v132, 1.0, v128
	v_add_f32_e32 v137, 1.0, v133
	v_mul_f32_e32 v131, v128, v131
	v_mul_f32_e32 v136, v133, v136
	v_log_f32_e32 v132, v132
	v_log_f32_e32 v137, v137
	v_mul_f32_e32 v128, 0xbf317217, v132
	v_mul_f32_e32 v133, 0xbf317217, v137
	v_fmac_f32_e32 v128, 0x3f317217, v132
	v_fmac_f32_e32 v133, 0x3f317217, v137
	v_fmac_f32_e32 v128, 0x3377d1cf, v132
	v_fmac_f32_e32 v133, 0x3377d1cf, v137
	v_fmac_f32_e32 v128, 0x3f317217, v132
	v_fmac_f32_e32 v133, 0x3f317217, v137
	v_cndmask_b32_e32 v131, v131, v128, vcc
	v_cndmask_b32_e64 v136, v136, v133, s[24:25]
	v_add_f32_e32 v116, v116, v131
	v_add_f32_e32 v100, v100, v136
	global_store_dword v134, v116, s[0:1] offset:2048
	global_store_dword v134, v100, s[0:1] offset:2176
	v_add_f32_e32 v117, v117, v138
	v_add_f32_e32 v101, v101, v139
	v_mul_f32_e32 v128, 0xbfb8aa3b, v117
	v_mul_f32_e32 v133, 0xbfb8aa3b, v101
	v_exp_f32_e64 v128, -|v128|
	v_exp_f32_e64 v133, -|v133|
	v_max_f32_e32 v117, 0, v117
	v_max_f32_e32 v101, 0, v101
	v_fma_f32 v131, v128, s101, 0.5
	v_fma_f32 v136, v133, s101, 0.5
	v_cmp_le_f32_e32 vcc, s100, v128
	v_cmp_le_f32_e64 s[24:25], s100, v133
	v_fma_f32 v131, -v128, v131, 1.0
	v_fma_f32 v136, -v133, v136, 1.0
	v_add_f32_e32 v132, 1.0, v128
	v_add_f32_e32 v137, 1.0, v133
	v_mul_f32_e32 v131, v128, v131
	v_mul_f32_e32 v136, v133, v136
	v_log_f32_e32 v132, v132
	v_log_f32_e32 v137, v137
	v_mul_f32_e32 v128, 0xbf317217, v132
	v_mul_f32_e32 v133, 0xbf317217, v137
	v_fmac_f32_e32 v128, 0x3f317217, v132
	v_fmac_f32_e32 v133, 0x3f317217, v137
	v_fmac_f32_e32 v128, 0x3377d1cf, v132
	v_fmac_f32_e32 v133, 0x3377d1cf, v137
	v_fmac_f32_e32 v128, 0x3f317217, v132
	v_fmac_f32_e32 v133, 0x3f317217, v137
	v_cndmask_b32_e32 v131, v131, v128, vcc
	v_cndmask_b32_e64 v136, v136, v133, s[24:25]
	v_add_f32_e32 v117, v117, v131
	v_add_f32_e32 v101, v101, v136
	global_store_dword v134, v117, s[0:1] offset:2304
	global_store_dword v134, v101, s[0:1] offset:2432
	v_add_f32_e32 v118, v118, v138
	v_add_f32_e32 v102, v102, v139
	v_mul_f32_e32 v128, 0xbfb8aa3b, v118
	v_mul_f32_e32 v133, 0xbfb8aa3b, v102
	v_exp_f32_e64 v128, -|v128|
	v_exp_f32_e64 v133, -|v133|
	v_max_f32_e32 v118, 0, v118
	v_max_f32_e32 v102, 0, v102
	v_fma_f32 v131, v128, s101, 0.5
	v_fma_f32 v136, v133, s101, 0.5
	v_cmp_le_f32_e32 vcc, s100, v128
	v_cmp_le_f32_e64 s[24:25], s100, v133
	v_fma_f32 v131, -v128, v131, 1.0
	v_fma_f32 v136, -v133, v136, 1.0
	v_add_f32_e32 v132, 1.0, v128
	v_add_f32_e32 v137, 1.0, v133
	v_mul_f32_e32 v131, v128, v131
	v_mul_f32_e32 v136, v133, v136
	v_log_f32_e32 v132, v132
	v_log_f32_e32 v137, v137
	v_mul_f32_e32 v128, 0xbf317217, v132
	v_mul_f32_e32 v133, 0xbf317217, v137
	v_fmac_f32_e32 v128, 0x3f317217, v132
	v_fmac_f32_e32 v133, 0x3f317217, v137
	v_fmac_f32_e32 v128, 0x3377d1cf, v132
	v_fmac_f32_e32 v133, 0x3377d1cf, v137
	v_fmac_f32_e32 v128, 0x3f317217, v132
	v_fmac_f32_e32 v133, 0x3f317217, v137
	v_cndmask_b32_e32 v131, v131, v128, vcc
	v_cndmask_b32_e64 v136, v136, v133, s[24:25]
	v_add_f32_e32 v118, v118, v131
	v_add_f32_e32 v102, v102, v136
	global_store_dword v134, v118, s[0:1] offset:2560
	global_store_dword v134, v102, s[0:1] offset:2688
	v_add_f32_e32 v119, v119, v138
	v_add_f32_e32 v103, v103, v139
	v_mul_f32_e32 v128, 0xbfb8aa3b, v119
	v_mul_f32_e32 v133, 0xbfb8aa3b, v103
	v_exp_f32_e64 v128, -|v128|
	v_exp_f32_e64 v133, -|v133|
	v_max_f32_e32 v119, 0, v119
	v_max_f32_e32 v103, 0, v103
	v_fma_f32 v131, v128, s101, 0.5
	v_fma_f32 v136, v133, s101, 0.5
	v_cmp_le_f32_e32 vcc, s100, v128
	v_cmp_le_f32_e64 s[24:25], s100, v133
	v_fma_f32 v131, -v128, v131, 1.0
	v_fma_f32 v136, -v133, v136, 1.0
	v_add_f32_e32 v132, 1.0, v128
	v_add_f32_e32 v137, 1.0, v133
	v_mul_f32_e32 v131, v128, v131
	v_mul_f32_e32 v136, v133, v136
	v_log_f32_e32 v132, v132
	v_log_f32_e32 v137, v137
	v_mul_f32_e32 v128, 0xbf317217, v132
	v_mul_f32_e32 v133, 0xbf317217, v137
	v_fmac_f32_e32 v128, 0x3f317217, v132
	v_fmac_f32_e32 v133, 0x3f317217, v137
	v_fmac_f32_e32 v128, 0x3377d1cf, v132
	v_fmac_f32_e32 v133, 0x3377d1cf, v137
	v_fmac_f32_e32 v128, 0x3f317217, v132
	v_fmac_f32_e32 v133, 0x3f317217, v137
	v_cndmask_b32_e32 v131, v131, v128, vcc
	v_cndmask_b32_e64 v136, v136, v133, s[24:25]
	v_add_f32_e32 v119, v119, v131
	v_add_f32_e32 v103, v103, v136
	global_store_dword v134, v119, s[0:1] offset:2816
	global_store_dword v134, v103, s[0:1] offset:2944
	s_add_u32 s0, s12, 0x1000
	s_addc_u32 s1, s13, 0
	v_add_f32_e32 v120, v120, v138
	v_add_f32_e32 v104, v104, v139
	v_mul_f32_e32 v128, 0xbfb8aa3b, v120
	v_mul_f32_e32 v133, 0xbfb8aa3b, v104
	v_exp_f32_e64 v128, -|v128|
	v_exp_f32_e64 v133, -|v133|
	v_max_f32_e32 v120, 0, v120
	v_max_f32_e32 v104, 0, v104
	v_fma_f32 v131, v128, s101, 0.5
	v_fma_f32 v136, v133, s101, 0.5
	v_cmp_le_f32_e32 vcc, s100, v128
	v_cmp_le_f32_e64 s[24:25], s100, v133
	v_fma_f32 v131, -v128, v131, 1.0
	v_fma_f32 v136, -v133, v136, 1.0
	v_add_f32_e32 v132, 1.0, v128
	v_add_f32_e32 v137, 1.0, v133
	v_mul_f32_e32 v131, v128, v131
	v_mul_f32_e32 v136, v133, v136
	v_log_f32_e32 v132, v132
	v_log_f32_e32 v137, v137
	v_mul_f32_e32 v128, 0xbf317217, v132
	v_mul_f32_e32 v133, 0xbf317217, v137
	v_fmac_f32_e32 v128, 0x3f317217, v132
	v_fmac_f32_e32 v133, 0x3f317217, v137
	v_fmac_f32_e32 v128, 0x3377d1cf, v132
	v_fmac_f32_e32 v133, 0x3377d1cf, v137
	v_fmac_f32_e32 v128, 0x3f317217, v132
	v_fmac_f32_e32 v133, 0x3f317217, v137
	v_cndmask_b32_e32 v131, v131, v128, vcc
	v_cndmask_b32_e64 v136, v136, v133, s[24:25]
	v_add_f32_e32 v120, v120, v131
	v_add_f32_e32 v104, v104, v136
	global_store_dword v134, v120, s[0:1]
	global_store_dword v134, v104, s[0:1] offset:128
	v_add_f32_e32 v121, v121, v138
	v_add_f32_e32 v105, v105, v139
	v_mul_f32_e32 v128, 0xbfb8aa3b, v121
	v_mul_f32_e32 v133, 0xbfb8aa3b, v105
	v_exp_f32_e64 v128, -|v128|
	v_exp_f32_e64 v133, -|v133|
	v_max_f32_e32 v121, 0, v121
	v_max_f32_e32 v105, 0, v105
	v_fma_f32 v131, v128, s101, 0.5
	v_fma_f32 v136, v133, s101, 0.5
	v_cmp_le_f32_e32 vcc, s100, v128
	v_cmp_le_f32_e64 s[24:25], s100, v133
	v_fma_f32 v131, -v128, v131, 1.0
	v_fma_f32 v136, -v133, v136, 1.0
	v_add_f32_e32 v132, 1.0, v128
	v_add_f32_e32 v137, 1.0, v133
	v_mul_f32_e32 v131, v128, v131
	v_mul_f32_e32 v136, v133, v136
	v_log_f32_e32 v132, v132
	v_log_f32_e32 v137, v137
	v_mul_f32_e32 v128, 0xbf317217, v132
	v_mul_f32_e32 v133, 0xbf317217, v137
	v_fmac_f32_e32 v128, 0x3f317217, v132
	v_fmac_f32_e32 v133, 0x3f317217, v137
	v_fmac_f32_e32 v128, 0x3377d1cf, v132
	v_fmac_f32_e32 v133, 0x3377d1cf, v137
	v_fmac_f32_e32 v128, 0x3f317217, v132
	v_fmac_f32_e32 v133, 0x3f317217, v137
	v_cndmask_b32_e32 v131, v131, v128, vcc
	v_cndmask_b32_e64 v136, v136, v133, s[24:25]
	v_add_f32_e32 v121, v121, v131
	v_add_f32_e32 v105, v105, v136
	global_store_dword v134, v121, s[0:1] offset:256
	global_store_dword v134, v105, s[0:1] offset:384
	v_add_f32_e32 v122, v122, v138
	v_add_f32_e32 v106, v106, v139
	v_mul_f32_e32 v128, 0xbfb8aa3b, v122
	v_mul_f32_e32 v133, 0xbfb8aa3b, v106
	v_exp_f32_e64 v128, -|v128|
	v_exp_f32_e64 v133, -|v133|
	v_max_f32_e32 v122, 0, v122
	v_max_f32_e32 v106, 0, v106
	v_fma_f32 v131, v128, s101, 0.5
	v_fma_f32 v136, v133, s101, 0.5
	v_cmp_le_f32_e32 vcc, s100, v128
	v_cmp_le_f32_e64 s[24:25], s100, v133
	v_fma_f32 v131, -v128, v131, 1.0
	v_fma_f32 v136, -v133, v136, 1.0
	v_add_f32_e32 v132, 1.0, v128
	v_add_f32_e32 v137, 1.0, v133
	v_mul_f32_e32 v131, v128, v131
	v_mul_f32_e32 v136, v133, v136
	v_log_f32_e32 v132, v132
	v_log_f32_e32 v137, v137
	v_mul_f32_e32 v128, 0xbf317217, v132
	v_mul_f32_e32 v133, 0xbf317217, v137
	v_fmac_f32_e32 v128, 0x3f317217, v132
	v_fmac_f32_e32 v133, 0x3f317217, v137
	v_fmac_f32_e32 v128, 0x3377d1cf, v132
	v_fmac_f32_e32 v133, 0x3377d1cf, v137
	v_fmac_f32_e32 v128, 0x3f317217, v132
	v_fmac_f32_e32 v133, 0x3f317217, v137
	v_cndmask_b32_e32 v131, v131, v128, vcc
	v_cndmask_b32_e64 v136, v136, v133, s[24:25]
	v_add_f32_e32 v122, v122, v131
	v_add_f32_e32 v106, v106, v136
	global_store_dword v134, v122, s[0:1] offset:512
	global_store_dword v134, v106, s[0:1] offset:640
	v_add_f32_e32 v123, v123, v138
	v_add_f32_e32 v107, v107, v139
	v_mul_f32_e32 v128, 0xbfb8aa3b, v123
	v_mul_f32_e32 v133, 0xbfb8aa3b, v107
	v_exp_f32_e64 v128, -|v128|
	v_exp_f32_e64 v133, -|v133|
	v_max_f32_e32 v123, 0, v123
	v_max_f32_e32 v107, 0, v107
	v_fma_f32 v131, v128, s101, 0.5
	v_fma_f32 v136, v133, s101, 0.5
	v_cmp_le_f32_e32 vcc, s100, v128
	v_cmp_le_f32_e64 s[24:25], s100, v133
	v_fma_f32 v131, -v128, v131, 1.0
	v_fma_f32 v136, -v133, v136, 1.0
	v_add_f32_e32 v132, 1.0, v128
	v_add_f32_e32 v137, 1.0, v133
	v_mul_f32_e32 v131, v128, v131
	v_mul_f32_e32 v136, v133, v136
	v_log_f32_e32 v132, v132
	v_log_f32_e32 v137, v137
	v_mul_f32_e32 v128, 0xbf317217, v132
	v_mul_f32_e32 v133, 0xbf317217, v137
	v_fmac_f32_e32 v128, 0x3f317217, v132
	v_fmac_f32_e32 v133, 0x3f317217, v137
	v_fmac_f32_e32 v128, 0x3377d1cf, v132
	v_fmac_f32_e32 v133, 0x3377d1cf, v137
	v_fmac_f32_e32 v128, 0x3f317217, v132
	v_fmac_f32_e32 v133, 0x3f317217, v137
	v_cndmask_b32_e32 v131, v131, v128, vcc
	v_cndmask_b32_e64 v136, v136, v133, s[24:25]
	v_add_f32_e32 v123, v123, v131
	v_add_f32_e32 v107, v107, v136
	global_store_dword v134, v123, s[0:1] offset:768
	global_store_dword v134, v107, s[0:1] offset:896
	v_add_f32_e32 v124, v124, v138
	v_add_f32_e32 v108, v108, v139
	v_mul_f32_e32 v128, 0xbfb8aa3b, v124
	v_mul_f32_e32 v133, 0xbfb8aa3b, v108
	v_exp_f32_e64 v128, -|v128|
	v_exp_f32_e64 v133, -|v133|
	v_max_f32_e32 v124, 0, v124
	v_max_f32_e32 v108, 0, v108
	v_fma_f32 v131, v128, s101, 0.5
	v_fma_f32 v136, v133, s101, 0.5
	v_cmp_le_f32_e32 vcc, s100, v128
	v_cmp_le_f32_e64 s[24:25], s100, v133
	v_fma_f32 v131, -v128, v131, 1.0
	v_fma_f32 v136, -v133, v136, 1.0
	v_add_f32_e32 v132, 1.0, v128
	v_add_f32_e32 v137, 1.0, v133
	v_mul_f32_e32 v131, v128, v131
	v_mul_f32_e32 v136, v133, v136
	v_log_f32_e32 v132, v132
	v_log_f32_e32 v137, v137
	v_mul_f32_e32 v128, 0xbf317217, v132
	v_mul_f32_e32 v133, 0xbf317217, v137
	v_fmac_f32_e32 v128, 0x3f317217, v132
	v_fmac_f32_e32 v133, 0x3f317217, v137
	v_fmac_f32_e32 v128, 0x3377d1cf, v132
	v_fmac_f32_e32 v133, 0x3377d1cf, v137
	v_fmac_f32_e32 v128, 0x3f317217, v132
	v_fmac_f32_e32 v133, 0x3f317217, v137
	v_cndmask_b32_e32 v131, v131, v128, vcc
	v_cndmask_b32_e64 v136, v136, v133, s[24:25]
	v_add_f32_e32 v124, v124, v131
	v_add_f32_e32 v108, v108, v136
	global_store_dword v134, v124, s[0:1] offset:2048
	global_store_dword v134, v108, s[0:1] offset:2176
	v_add_f32_e32 v125, v125, v138
	v_add_f32_e32 v109, v109, v139
	v_mul_f32_e32 v128, 0xbfb8aa3b, v125
	v_mul_f32_e32 v133, 0xbfb8aa3b, v109
	v_exp_f32_e64 v128, -|v128|
	v_exp_f32_e64 v133, -|v133|
	v_max_f32_e32 v125, 0, v125
	v_max_f32_e32 v109, 0, v109
	v_fma_f32 v131, v128, s101, 0.5
	v_fma_f32 v136, v133, s101, 0.5
	v_cmp_le_f32_e32 vcc, s100, v128
	v_cmp_le_f32_e64 s[24:25], s100, v133
	v_fma_f32 v131, -v128, v131, 1.0
	v_fma_f32 v136, -v133, v136, 1.0
	v_add_f32_e32 v132, 1.0, v128
	v_add_f32_e32 v137, 1.0, v133
	v_mul_f32_e32 v131, v128, v131
	v_mul_f32_e32 v136, v133, v136
	v_log_f32_e32 v132, v132
	v_log_f32_e32 v137, v137
	v_mul_f32_e32 v128, 0xbf317217, v132
	v_mul_f32_e32 v133, 0xbf317217, v137
	v_fmac_f32_e32 v128, 0x3f317217, v132
	v_fmac_f32_e32 v133, 0x3f317217, v137
	v_fmac_f32_e32 v128, 0x3377d1cf, v132
	v_fmac_f32_e32 v133, 0x3377d1cf, v137
	v_fmac_f32_e32 v128, 0x3f317217, v132
	v_fmac_f32_e32 v133, 0x3f317217, v137
	v_cndmask_b32_e32 v131, v131, v128, vcc
	v_cndmask_b32_e64 v136, v136, v133, s[24:25]
	v_add_f32_e32 v125, v125, v131
	v_add_f32_e32 v109, v109, v136
	global_store_dword v134, v125, s[0:1] offset:2304
	global_store_dword v134, v109, s[0:1] offset:2432
	v_add_f32_e32 v126, v126, v138
	v_add_f32_e32 v110, v110, v139
	v_mul_f32_e32 v128, 0xbfb8aa3b, v126
	v_mul_f32_e32 v133, 0xbfb8aa3b, v110
	v_exp_f32_e64 v128, -|v128|
	v_exp_f32_e64 v133, -|v133|
	v_max_f32_e32 v126, 0, v126
	v_max_f32_e32 v110, 0, v110
	v_fma_f32 v131, v128, s101, 0.5
	v_fma_f32 v136, v133, s101, 0.5
	v_cmp_le_f32_e32 vcc, s100, v128
	v_cmp_le_f32_e64 s[24:25], s100, v133
	v_fma_f32 v131, -v128, v131, 1.0
	v_fma_f32 v136, -v133, v136, 1.0
	v_add_f32_e32 v132, 1.0, v128
	v_add_f32_e32 v137, 1.0, v133
	v_mul_f32_e32 v131, v128, v131
	v_mul_f32_e32 v136, v133, v136
	v_log_f32_e32 v132, v132
	v_log_f32_e32 v137, v137
	v_mul_f32_e32 v128, 0xbf317217, v132
	v_mul_f32_e32 v133, 0xbf317217, v137
	v_fmac_f32_e32 v128, 0x3f317217, v132
	v_fmac_f32_e32 v133, 0x3f317217, v137
	v_fmac_f32_e32 v128, 0x3377d1cf, v132
	v_fmac_f32_e32 v133, 0x3377d1cf, v137
	v_fmac_f32_e32 v128, 0x3f317217, v132
	v_fmac_f32_e32 v133, 0x3f317217, v137
	v_cndmask_b32_e32 v131, v131, v128, vcc
	v_cndmask_b32_e64 v136, v136, v133, s[24:25]
	v_add_f32_e32 v126, v126, v131
	v_add_f32_e32 v110, v110, v136
	global_store_dword v134, v126, s[0:1] offset:2560
	global_store_dword v134, v110, s[0:1] offset:2688
	v_add_f32_e32 v127, v127, v138
	v_add_f32_e32 v111, v111, v139
	v_mul_f32_e32 v128, 0xbfb8aa3b, v127
	v_mul_f32_e32 v133, 0xbfb8aa3b, v111
	v_exp_f32_e64 v128, -|v128|
	v_exp_f32_e64 v133, -|v133|
	v_max_f32_e32 v127, 0, v127
	v_max_f32_e32 v111, 0, v111
	v_fma_f32 v131, v128, s101, 0.5
	v_fma_f32 v136, v133, s101, 0.5
	v_cmp_le_f32_e32 vcc, s100, v128
	v_cmp_le_f32_e64 s[24:25], s100, v133
	v_fma_f32 v131, -v128, v131, 1.0
	v_fma_f32 v136, -v133, v136, 1.0
	v_add_f32_e32 v132, 1.0, v128
	v_add_f32_e32 v137, 1.0, v133
	v_mul_f32_e32 v131, v128, v131
	v_mul_f32_e32 v136, v133, v136
	v_log_f32_e32 v132, v132
	v_log_f32_e32 v137, v137
	v_mul_f32_e32 v128, 0xbf317217, v132
	v_mul_f32_e32 v133, 0xbf317217, v137
	v_fmac_f32_e32 v128, 0x3f317217, v132
	v_fmac_f32_e32 v133, 0x3f317217, v137
	v_fmac_f32_e32 v128, 0x3377d1cf, v132
	v_fmac_f32_e32 v133, 0x3377d1cf, v137
	v_fmac_f32_e32 v128, 0x3f317217, v132
	v_fmac_f32_e32 v133, 0x3f317217, v137
	v_cndmask_b32_e32 v131, v131, v128, vcc
	v_cndmask_b32_e64 v136, v136, v133, s[24:25]
	v_add_f32_e32 v127, v127, v131
	v_add_f32_e32 v111, v111, v136
	global_store_dword v134, v127, s[0:1] offset:2816
	global_store_dword v134, v111, s[0:1] offset:2944
	s_add_u32 s0, s12, 0x2000
	s_addc_u32 s1, s13, 0
	v_add_f32_e32 v80, v80, v138
	v_add_f32_e32 v64, v64, v139
	v_mul_f32_e32 v128, 0xbfb8aa3b, v80
	v_mul_f32_e32 v133, 0xbfb8aa3b, v64
	v_exp_f32_e64 v128, -|v128|
	v_exp_f32_e64 v133, -|v133|
	v_max_f32_e32 v80, 0, v80
	v_max_f32_e32 v64, 0, v64
	v_fma_f32 v131, v128, s101, 0.5
	v_fma_f32 v136, v133, s101, 0.5
	v_cmp_le_f32_e32 vcc, s100, v128
	v_cmp_le_f32_e64 s[24:25], s100, v133
	v_fma_f32 v131, -v128, v131, 1.0
	v_fma_f32 v136, -v133, v136, 1.0
	v_add_f32_e32 v132, 1.0, v128
	v_add_f32_e32 v137, 1.0, v133
	v_mul_f32_e32 v131, v128, v131
	v_mul_f32_e32 v136, v133, v136
	v_log_f32_e32 v132, v132
	v_log_f32_e32 v137, v137
	v_mul_f32_e32 v128, 0xbf317217, v132
	v_mul_f32_e32 v133, 0xbf317217, v137
	v_fmac_f32_e32 v128, 0x3f317217, v132
	v_fmac_f32_e32 v133, 0x3f317217, v137
	v_fmac_f32_e32 v128, 0x3377d1cf, v132
	v_fmac_f32_e32 v133, 0x3377d1cf, v137
	v_fmac_f32_e32 v128, 0x3f317217, v132
	v_fmac_f32_e32 v133, 0x3f317217, v137
	v_cndmask_b32_e32 v131, v131, v128, vcc
	v_cndmask_b32_e64 v136, v136, v133, s[24:25]
	v_add_f32_e32 v80, v80, v131
	v_add_f32_e32 v64, v64, v136
	global_store_dword v134, v80, s[0:1]
	global_store_dword v134, v64, s[0:1] offset:128
	v_add_f32_e32 v81, v81, v138
	v_add_f32_e32 v65, v65, v139
	v_mul_f32_e32 v128, 0xbfb8aa3b, v81
	v_mul_f32_e32 v133, 0xbfb8aa3b, v65
	v_exp_f32_e64 v128, -|v128|
	v_exp_f32_e64 v133, -|v133|
	v_max_f32_e32 v81, 0, v81
	v_max_f32_e32 v65, 0, v65
	v_fma_f32 v131, v128, s101, 0.5
	v_fma_f32 v136, v133, s101, 0.5
	v_cmp_le_f32_e32 vcc, s100, v128
	v_cmp_le_f32_e64 s[24:25], s100, v133
	v_fma_f32 v131, -v128, v131, 1.0
	v_fma_f32 v136, -v133, v136, 1.0
	v_add_f32_e32 v132, 1.0, v128
	v_add_f32_e32 v137, 1.0, v133
	v_mul_f32_e32 v131, v128, v131
	v_mul_f32_e32 v136, v133, v136
	v_log_f32_e32 v132, v132
	v_log_f32_e32 v137, v137
	v_mul_f32_e32 v128, 0xbf317217, v132
	v_mul_f32_e32 v133, 0xbf317217, v137
	v_fmac_f32_e32 v128, 0x3f317217, v132
	v_fmac_f32_e32 v133, 0x3f317217, v137
	v_fmac_f32_e32 v128, 0x3377d1cf, v132
	v_fmac_f32_e32 v133, 0x3377d1cf, v137
	v_fmac_f32_e32 v128, 0x3f317217, v132
	v_fmac_f32_e32 v133, 0x3f317217, v137
	v_cndmask_b32_e32 v131, v131, v128, vcc
	v_cndmask_b32_e64 v136, v136, v133, s[24:25]
	v_add_f32_e32 v81, v81, v131
	v_add_f32_e32 v65, v65, v136
	global_store_dword v134, v81, s[0:1] offset:256
	global_store_dword v134, v65, s[0:1] offset:384
	v_add_f32_e32 v82, v82, v138
	v_add_f32_e32 v66, v66, v139
	v_mul_f32_e32 v128, 0xbfb8aa3b, v82
	v_mul_f32_e32 v133, 0xbfb8aa3b, v66
	v_exp_f32_e64 v128, -|v128|
	v_exp_f32_e64 v133, -|v133|
	v_max_f32_e32 v82, 0, v82
	v_max_f32_e32 v66, 0, v66
	v_fma_f32 v131, v128, s101, 0.5
	v_fma_f32 v136, v133, s101, 0.5
	v_cmp_le_f32_e32 vcc, s100, v128
	v_cmp_le_f32_e64 s[24:25], s100, v133
	v_fma_f32 v131, -v128, v131, 1.0
	v_fma_f32 v136, -v133, v136, 1.0
	v_add_f32_e32 v132, 1.0, v128
	v_add_f32_e32 v137, 1.0, v133
	v_mul_f32_e32 v131, v128, v131
	v_mul_f32_e32 v136, v133, v136
	v_log_f32_e32 v132, v132
	v_log_f32_e32 v137, v137
	v_mul_f32_e32 v128, 0xbf317217, v132
	v_mul_f32_e32 v133, 0xbf317217, v137
	v_fmac_f32_e32 v128, 0x3f317217, v132
	v_fmac_f32_e32 v133, 0x3f317217, v137
	v_fmac_f32_e32 v128, 0x3377d1cf, v132
	v_fmac_f32_e32 v133, 0x3377d1cf, v137
	v_fmac_f32_e32 v128, 0x3f317217, v132
	v_fmac_f32_e32 v133, 0x3f317217, v137
	v_cndmask_b32_e32 v131, v131, v128, vcc
	v_cndmask_b32_e64 v136, v136, v133, s[24:25]
	v_add_f32_e32 v82, v82, v131
	v_add_f32_e32 v66, v66, v136
	global_store_dword v134, v82, s[0:1] offset:512
	global_store_dword v134, v66, s[0:1] offset:640
	v_add_f32_e32 v83, v83, v138
	v_add_f32_e32 v67, v67, v139
	v_mul_f32_e32 v128, 0xbfb8aa3b, v83
	v_mul_f32_e32 v133, 0xbfb8aa3b, v67
	v_exp_f32_e64 v128, -|v128|
	v_exp_f32_e64 v133, -|v133|
	v_max_f32_e32 v83, 0, v83
	v_max_f32_e32 v67, 0, v67
	v_fma_f32 v131, v128, s101, 0.5
	v_fma_f32 v136, v133, s101, 0.5
	v_cmp_le_f32_e32 vcc, s100, v128
	v_cmp_le_f32_e64 s[24:25], s100, v133
	v_fma_f32 v131, -v128, v131, 1.0
	v_fma_f32 v136, -v133, v136, 1.0
	v_add_f32_e32 v132, 1.0, v128
	v_add_f32_e32 v137, 1.0, v133
	v_mul_f32_e32 v131, v128, v131
	v_mul_f32_e32 v136, v133, v136
	v_log_f32_e32 v132, v132
	v_log_f32_e32 v137, v137
	v_mul_f32_e32 v128, 0xbf317217, v132
	v_mul_f32_e32 v133, 0xbf317217, v137
	v_fmac_f32_e32 v128, 0x3f317217, v132
	v_fmac_f32_e32 v133, 0x3f317217, v137
	v_fmac_f32_e32 v128, 0x3377d1cf, v132
	v_fmac_f32_e32 v133, 0x3377d1cf, v137
	v_fmac_f32_e32 v128, 0x3f317217, v132
	v_fmac_f32_e32 v133, 0x3f317217, v137
	v_cndmask_b32_e32 v131, v131, v128, vcc
	v_cndmask_b32_e64 v136, v136, v133, s[24:25]
	v_add_f32_e32 v83, v83, v131
	v_add_f32_e32 v67, v67, v136
	global_store_dword v134, v83, s[0:1] offset:768
	global_store_dword v134, v67, s[0:1] offset:896
	v_add_f32_e32 v84, v84, v138
	v_add_f32_e32 v68, v68, v139
	v_mul_f32_e32 v128, 0xbfb8aa3b, v84
	v_mul_f32_e32 v133, 0xbfb8aa3b, v68
	v_exp_f32_e64 v128, -|v128|
	v_exp_f32_e64 v133, -|v133|
	v_max_f32_e32 v84, 0, v84
	v_max_f32_e32 v68, 0, v68
	v_fma_f32 v131, v128, s101, 0.5
	v_fma_f32 v136, v133, s101, 0.5
	v_cmp_le_f32_e32 vcc, s100, v128
	v_cmp_le_f32_e64 s[24:25], s100, v133
	v_fma_f32 v131, -v128, v131, 1.0
	v_fma_f32 v136, -v133, v136, 1.0
	v_add_f32_e32 v132, 1.0, v128
	v_add_f32_e32 v137, 1.0, v133
	v_mul_f32_e32 v131, v128, v131
	v_mul_f32_e32 v136, v133, v136
	v_log_f32_e32 v132, v132
	v_log_f32_e32 v137, v137
	v_mul_f32_e32 v128, 0xbf317217, v132
	v_mul_f32_e32 v133, 0xbf317217, v137
	v_fmac_f32_e32 v128, 0x3f317217, v132
	v_fmac_f32_e32 v133, 0x3f317217, v137
	v_fmac_f32_e32 v128, 0x3377d1cf, v132
	v_fmac_f32_e32 v133, 0x3377d1cf, v137
	v_fmac_f32_e32 v128, 0x3f317217, v132
	v_fmac_f32_e32 v133, 0x3f317217, v137
	v_cndmask_b32_e32 v131, v131, v128, vcc
	v_cndmask_b32_e64 v136, v136, v133, s[24:25]
	v_add_f32_e32 v84, v84, v131
	v_add_f32_e32 v68, v68, v136
	global_store_dword v134, v84, s[0:1] offset:2048
	global_store_dword v134, v68, s[0:1] offset:2176
	v_add_f32_e32 v85, v85, v138
	v_add_f32_e32 v69, v69, v139
	v_mul_f32_e32 v128, 0xbfb8aa3b, v85
	v_mul_f32_e32 v133, 0xbfb8aa3b, v69
	v_exp_f32_e64 v128, -|v128|
	v_exp_f32_e64 v133, -|v133|
	v_max_f32_e32 v85, 0, v85
	v_max_f32_e32 v69, 0, v69
	v_fma_f32 v131, v128, s101, 0.5
	v_fma_f32 v136, v133, s101, 0.5
	v_cmp_le_f32_e32 vcc, s100, v128
	v_cmp_le_f32_e64 s[24:25], s100, v133
	v_fma_f32 v131, -v128, v131, 1.0
	v_fma_f32 v136, -v133, v136, 1.0
	v_add_f32_e32 v132, 1.0, v128
	v_add_f32_e32 v137, 1.0, v133
	v_mul_f32_e32 v131, v128, v131
	v_mul_f32_e32 v136, v133, v136
	v_log_f32_e32 v132, v132
	v_log_f32_e32 v137, v137
	v_mul_f32_e32 v128, 0xbf317217, v132
	v_mul_f32_e32 v133, 0xbf317217, v137
	v_fmac_f32_e32 v128, 0x3f317217, v132
	v_fmac_f32_e32 v133, 0x3f317217, v137
	v_fmac_f32_e32 v128, 0x3377d1cf, v132
	v_fmac_f32_e32 v133, 0x3377d1cf, v137
	v_fmac_f32_e32 v128, 0x3f317217, v132
	v_fmac_f32_e32 v133, 0x3f317217, v137
	v_cndmask_b32_e32 v131, v131, v128, vcc
	v_cndmask_b32_e64 v136, v136, v133, s[24:25]
	v_add_f32_e32 v85, v85, v131
	v_add_f32_e32 v69, v69, v136
	global_store_dword v134, v85, s[0:1] offset:2304
	global_store_dword v134, v69, s[0:1] offset:2432
	v_add_f32_e32 v86, v86, v138
	v_add_f32_e32 v70, v70, v139
	v_mul_f32_e32 v128, 0xbfb8aa3b, v86
	v_mul_f32_e32 v133, 0xbfb8aa3b, v70
	v_exp_f32_e64 v128, -|v128|
	v_exp_f32_e64 v133, -|v133|
	v_max_f32_e32 v86, 0, v86
	v_max_f32_e32 v70, 0, v70
	v_fma_f32 v131, v128, s101, 0.5
	v_fma_f32 v136, v133, s101, 0.5
	v_cmp_le_f32_e32 vcc, s100, v128
	v_cmp_le_f32_e64 s[24:25], s100, v133
	v_fma_f32 v131, -v128, v131, 1.0
	v_fma_f32 v136, -v133, v136, 1.0
	v_add_f32_e32 v132, 1.0, v128
	v_add_f32_e32 v137, 1.0, v133
	v_mul_f32_e32 v131, v128, v131
	v_mul_f32_e32 v136, v133, v136
	v_log_f32_e32 v132, v132
	v_log_f32_e32 v137, v137
	v_mul_f32_e32 v128, 0xbf317217, v132
	v_mul_f32_e32 v133, 0xbf317217, v137
	v_fmac_f32_e32 v128, 0x3f317217, v132
	v_fmac_f32_e32 v133, 0x3f317217, v137
	v_fmac_f32_e32 v128, 0x3377d1cf, v132
	v_fmac_f32_e32 v133, 0x3377d1cf, v137
	v_fmac_f32_e32 v128, 0x3f317217, v132
	v_fmac_f32_e32 v133, 0x3f317217, v137
	v_cndmask_b32_e32 v131, v131, v128, vcc
	v_cndmask_b32_e64 v136, v136, v133, s[24:25]
	v_add_f32_e32 v86, v86, v131
	v_add_f32_e32 v70, v70, v136
	global_store_dword v134, v86, s[0:1] offset:2560
	global_store_dword v134, v70, s[0:1] offset:2688
	v_add_f32_e32 v87, v87, v138
	v_add_f32_e32 v71, v71, v139
	v_mul_f32_e32 v128, 0xbfb8aa3b, v87
	v_mul_f32_e32 v133, 0xbfb8aa3b, v71
	v_exp_f32_e64 v128, -|v128|
	v_exp_f32_e64 v133, -|v133|
	v_max_f32_e32 v87, 0, v87
	v_max_f32_e32 v71, 0, v71
	v_fma_f32 v131, v128, s101, 0.5
	v_fma_f32 v136, v133, s101, 0.5
	v_cmp_le_f32_e32 vcc, s100, v128
	v_cmp_le_f32_e64 s[24:25], s100, v133
	v_fma_f32 v131, -v128, v131, 1.0
	v_fma_f32 v136, -v133, v136, 1.0
	v_add_f32_e32 v132, 1.0, v128
	v_add_f32_e32 v137, 1.0, v133
	v_mul_f32_e32 v131, v128, v131
	v_mul_f32_e32 v136, v133, v136
	v_log_f32_e32 v132, v132
	v_log_f32_e32 v137, v137
	v_mul_f32_e32 v128, 0xbf317217, v132
	v_mul_f32_e32 v133, 0xbf317217, v137
	v_fmac_f32_e32 v128, 0x3f317217, v132
	v_fmac_f32_e32 v133, 0x3f317217, v137
	v_fmac_f32_e32 v128, 0x3377d1cf, v132
	v_fmac_f32_e32 v133, 0x3377d1cf, v137
	v_fmac_f32_e32 v128, 0x3f317217, v132
	v_fmac_f32_e32 v133, 0x3f317217, v137
	v_cndmask_b32_e32 v131, v131, v128, vcc
	v_cndmask_b32_e64 v136, v136, v133, s[24:25]
	v_add_f32_e32 v87, v87, v131
	v_add_f32_e32 v71, v71, v136
	global_store_dword v134, v87, s[0:1] offset:2816
	global_store_dword v134, v71, s[0:1] offset:2944
	s_add_u32 s0, s12, 0x3000
	s_addc_u32 s1, s13, 0
	v_add_f32_e32 v88, v88, v138
	v_add_f32_e32 v72, v72, v139
	v_mul_f32_e32 v128, 0xbfb8aa3b, v88
	v_mul_f32_e32 v133, 0xbfb8aa3b, v72
	v_exp_f32_e64 v128, -|v128|
	v_exp_f32_e64 v133, -|v133|
	v_max_f32_e32 v88, 0, v88
	v_max_f32_e32 v72, 0, v72
	v_fma_f32 v131, v128, s101, 0.5
	v_fma_f32 v136, v133, s101, 0.5
	v_cmp_le_f32_e32 vcc, s100, v128
	v_cmp_le_f32_e64 s[24:25], s100, v133
	v_fma_f32 v131, -v128, v131, 1.0
	v_fma_f32 v136, -v133, v136, 1.0
	v_add_f32_e32 v132, 1.0, v128
	v_add_f32_e32 v137, 1.0, v133
	v_mul_f32_e32 v131, v128, v131
	v_mul_f32_e32 v136, v133, v136
	v_log_f32_e32 v132, v132
	v_log_f32_e32 v137, v137
	v_mul_f32_e32 v128, 0xbf317217, v132
	v_mul_f32_e32 v133, 0xbf317217, v137
	v_fmac_f32_e32 v128, 0x3f317217, v132
	v_fmac_f32_e32 v133, 0x3f317217, v137
	v_fmac_f32_e32 v128, 0x3377d1cf, v132
	v_fmac_f32_e32 v133, 0x3377d1cf, v137
	v_fmac_f32_e32 v128, 0x3f317217, v132
	v_fmac_f32_e32 v133, 0x3f317217, v137
	v_cndmask_b32_e32 v131, v131, v128, vcc
	v_cndmask_b32_e64 v136, v136, v133, s[24:25]
	v_add_f32_e32 v88, v88, v131
	v_add_f32_e32 v72, v72, v136
	global_store_dword v134, v88, s[0:1]
	global_store_dword v134, v72, s[0:1] offset:128
	v_add_f32_e32 v89, v89, v138
	v_add_f32_e32 v73, v73, v139
	v_mul_f32_e32 v128, 0xbfb8aa3b, v89
	v_mul_f32_e32 v133, 0xbfb8aa3b, v73
	v_exp_f32_e64 v128, -|v128|
	v_exp_f32_e64 v133, -|v133|
	v_max_f32_e32 v89, 0, v89
	v_max_f32_e32 v73, 0, v73
	v_fma_f32 v131, v128, s101, 0.5
	v_fma_f32 v136, v133, s101, 0.5
	v_cmp_le_f32_e32 vcc, s100, v128
	v_cmp_le_f32_e64 s[24:25], s100, v133
	v_fma_f32 v131, -v128, v131, 1.0
	v_fma_f32 v136, -v133, v136, 1.0
	v_add_f32_e32 v132, 1.0, v128
	v_add_f32_e32 v137, 1.0, v133
	v_mul_f32_e32 v131, v128, v131
	v_mul_f32_e32 v136, v133, v136
	v_log_f32_e32 v132, v132
	v_log_f32_e32 v137, v137
	v_mul_f32_e32 v128, 0xbf317217, v132
	v_mul_f32_e32 v133, 0xbf317217, v137
	v_fmac_f32_e32 v128, 0x3f317217, v132
	v_fmac_f32_e32 v133, 0x3f317217, v137
	v_fmac_f32_e32 v128, 0x3377d1cf, v132
	v_fmac_f32_e32 v133, 0x3377d1cf, v137
	v_fmac_f32_e32 v128, 0x3f317217, v132
	v_fmac_f32_e32 v133, 0x3f317217, v137
	v_cndmask_b32_e32 v131, v131, v128, vcc
	v_cndmask_b32_e64 v136, v136, v133, s[24:25]
	v_add_f32_e32 v89, v89, v131
	v_add_f32_e32 v73, v73, v136
	global_store_dword v134, v89, s[0:1] offset:256
	global_store_dword v134, v73, s[0:1] offset:384
	v_add_f32_e32 v90, v90, v138
	v_add_f32_e32 v74, v74, v139
	v_mul_f32_e32 v128, 0xbfb8aa3b, v90
	v_mul_f32_e32 v133, 0xbfb8aa3b, v74
	v_exp_f32_e64 v128, -|v128|
	v_exp_f32_e64 v133, -|v133|
	v_max_f32_e32 v90, 0, v90
	v_max_f32_e32 v74, 0, v74
	v_fma_f32 v131, v128, s101, 0.5
	v_fma_f32 v136, v133, s101, 0.5
	v_cmp_le_f32_e32 vcc, s100, v128
	v_cmp_le_f32_e64 s[24:25], s100, v133
	v_fma_f32 v131, -v128, v131, 1.0
	v_fma_f32 v136, -v133, v136, 1.0
	v_add_f32_e32 v132, 1.0, v128
	v_add_f32_e32 v137, 1.0, v133
	v_mul_f32_e32 v131, v128, v131
	v_mul_f32_e32 v136, v133, v136
	v_log_f32_e32 v132, v132
	v_log_f32_e32 v137, v137
	v_mul_f32_e32 v128, 0xbf317217, v132
	v_mul_f32_e32 v133, 0xbf317217, v137
	v_fmac_f32_e32 v128, 0x3f317217, v132
	v_fmac_f32_e32 v133, 0x3f317217, v137
	v_fmac_f32_e32 v128, 0x3377d1cf, v132
	v_fmac_f32_e32 v133, 0x3377d1cf, v137
	v_fmac_f32_e32 v128, 0x3f317217, v132
	v_fmac_f32_e32 v133, 0x3f317217, v137
	v_cndmask_b32_e32 v131, v131, v128, vcc
	v_cndmask_b32_e64 v136, v136, v133, s[24:25]
	v_add_f32_e32 v90, v90, v131
	v_add_f32_e32 v74, v74, v136
	global_store_dword v134, v90, s[0:1] offset:512
	global_store_dword v134, v74, s[0:1] offset:640
	v_add_f32_e32 v91, v91, v138
	v_add_f32_e32 v75, v75, v139
	v_mul_f32_e32 v128, 0xbfb8aa3b, v91
	v_mul_f32_e32 v133, 0xbfb8aa3b, v75
	v_exp_f32_e64 v128, -|v128|
	v_exp_f32_e64 v133, -|v133|
	v_max_f32_e32 v91, 0, v91
	v_max_f32_e32 v75, 0, v75
	v_fma_f32 v131, v128, s101, 0.5
	v_fma_f32 v136, v133, s101, 0.5
	v_cmp_le_f32_e32 vcc, s100, v128
	v_cmp_le_f32_e64 s[24:25], s100, v133
	v_fma_f32 v131, -v128, v131, 1.0
	v_fma_f32 v136, -v133, v136, 1.0
	v_add_f32_e32 v132, 1.0, v128
	v_add_f32_e32 v137, 1.0, v133
	v_mul_f32_e32 v131, v128, v131
	v_mul_f32_e32 v136, v133, v136
	v_log_f32_e32 v132, v132
	v_log_f32_e32 v137, v137
	v_mul_f32_e32 v128, 0xbf317217, v132
	v_mul_f32_e32 v133, 0xbf317217, v137
	v_fmac_f32_e32 v128, 0x3f317217, v132
	v_fmac_f32_e32 v133, 0x3f317217, v137
	v_fmac_f32_e32 v128, 0x3377d1cf, v132
	v_fmac_f32_e32 v133, 0x3377d1cf, v137
	v_fmac_f32_e32 v128, 0x3f317217, v132
	v_fmac_f32_e32 v133, 0x3f317217, v137
	v_cndmask_b32_e32 v131, v131, v128, vcc
	v_cndmask_b32_e64 v136, v136, v133, s[24:25]
	v_add_f32_e32 v91, v91, v131
	v_add_f32_e32 v75, v75, v136
	global_store_dword v134, v91, s[0:1] offset:768
	global_store_dword v134, v75, s[0:1] offset:896
	v_add_f32_e32 v92, v92, v138
	v_add_f32_e32 v76, v76, v139
	v_mul_f32_e32 v128, 0xbfb8aa3b, v92
	v_mul_f32_e32 v133, 0xbfb8aa3b, v76
	v_exp_f32_e64 v128, -|v128|
	v_exp_f32_e64 v133, -|v133|
	v_max_f32_e32 v92, 0, v92
	v_max_f32_e32 v76, 0, v76
	v_fma_f32 v131, v128, s101, 0.5
	v_fma_f32 v136, v133, s101, 0.5
	v_cmp_le_f32_e32 vcc, s100, v128
	v_cmp_le_f32_e64 s[24:25], s100, v133
	v_fma_f32 v131, -v128, v131, 1.0
	v_fma_f32 v136, -v133, v136, 1.0
	v_add_f32_e32 v132, 1.0, v128
	v_add_f32_e32 v137, 1.0, v133
	v_mul_f32_e32 v131, v128, v131
	v_mul_f32_e32 v136, v133, v136
	v_log_f32_e32 v132, v132
	v_log_f32_e32 v137, v137
	v_mul_f32_e32 v128, 0xbf317217, v132
	v_mul_f32_e32 v133, 0xbf317217, v137
	v_fmac_f32_e32 v128, 0x3f317217, v132
	v_fmac_f32_e32 v133, 0x3f317217, v137
	v_fmac_f32_e32 v128, 0x3377d1cf, v132
	v_fmac_f32_e32 v133, 0x3377d1cf, v137
	v_fmac_f32_e32 v128, 0x3f317217, v132
	v_fmac_f32_e32 v133, 0x3f317217, v137
	v_cndmask_b32_e32 v131, v131, v128, vcc
	v_cndmask_b32_e64 v136, v136, v133, s[24:25]
	v_add_f32_e32 v92, v92, v131
	v_add_f32_e32 v76, v76, v136
	global_store_dword v134, v92, s[0:1] offset:2048
	global_store_dword v134, v76, s[0:1] offset:2176
	v_add_f32_e32 v93, v93, v138
	v_add_f32_e32 v77, v77, v139
	v_mul_f32_e32 v128, 0xbfb8aa3b, v93
	v_mul_f32_e32 v133, 0xbfb8aa3b, v77
	v_exp_f32_e64 v128, -|v128|
	v_exp_f32_e64 v133, -|v133|
	v_max_f32_e32 v93, 0, v93
	v_max_f32_e32 v77, 0, v77
	v_fma_f32 v131, v128, s101, 0.5
	v_fma_f32 v136, v133, s101, 0.5
	v_cmp_le_f32_e32 vcc, s100, v128
	v_cmp_le_f32_e64 s[24:25], s100, v133
	v_fma_f32 v131, -v128, v131, 1.0
	v_fma_f32 v136, -v133, v136, 1.0
	v_add_f32_e32 v132, 1.0, v128
	v_add_f32_e32 v137, 1.0, v133
	v_mul_f32_e32 v131, v128, v131
	v_mul_f32_e32 v136, v133, v136
	v_log_f32_e32 v132, v132
	v_log_f32_e32 v137, v137
	v_mul_f32_e32 v128, 0xbf317217, v132
	v_mul_f32_e32 v133, 0xbf317217, v137
	v_fmac_f32_e32 v128, 0x3f317217, v132
	v_fmac_f32_e32 v133, 0x3f317217, v137
	v_fmac_f32_e32 v128, 0x3377d1cf, v132
	v_fmac_f32_e32 v133, 0x3377d1cf, v137
	v_fmac_f32_e32 v128, 0x3f317217, v132
	v_fmac_f32_e32 v133, 0x3f317217, v137
	v_cndmask_b32_e32 v131, v131, v128, vcc
	v_cndmask_b32_e64 v136, v136, v133, s[24:25]
	v_add_f32_e32 v93, v93, v131
	v_add_f32_e32 v77, v77, v136
	global_store_dword v134, v93, s[0:1] offset:2304
	global_store_dword v134, v77, s[0:1] offset:2432
	v_add_f32_e32 v94, v94, v138
	v_add_f32_e32 v78, v78, v139
	v_mul_f32_e32 v128, 0xbfb8aa3b, v94
	v_mul_f32_e32 v133, 0xbfb8aa3b, v78
	v_exp_f32_e64 v128, -|v128|
	v_exp_f32_e64 v133, -|v133|
	v_max_f32_e32 v94, 0, v94
	v_max_f32_e32 v78, 0, v78
	v_fma_f32 v131, v128, s101, 0.5
	v_fma_f32 v136, v133, s101, 0.5
	v_cmp_le_f32_e32 vcc, s100, v128
	v_cmp_le_f32_e64 s[24:25], s100, v133
	v_fma_f32 v131, -v128, v131, 1.0
	v_fma_f32 v136, -v133, v136, 1.0
	v_add_f32_e32 v132, 1.0, v128
	v_add_f32_e32 v137, 1.0, v133
	v_mul_f32_e32 v131, v128, v131
	v_mul_f32_e32 v136, v133, v136
	v_log_f32_e32 v132, v132
	v_log_f32_e32 v137, v137
	v_mul_f32_e32 v128, 0xbf317217, v132
	v_mul_f32_e32 v133, 0xbf317217, v137
	v_fmac_f32_e32 v128, 0x3f317217, v132
	v_fmac_f32_e32 v133, 0x3f317217, v137
	v_fmac_f32_e32 v128, 0x3377d1cf, v132
	v_fmac_f32_e32 v133, 0x3377d1cf, v137
	v_fmac_f32_e32 v128, 0x3f317217, v132
	v_fmac_f32_e32 v133, 0x3f317217, v137
	v_cndmask_b32_e32 v131, v131, v128, vcc
	v_cndmask_b32_e64 v136, v136, v133, s[24:25]
	v_add_f32_e32 v94, v94, v131
	v_add_f32_e32 v78, v78, v136
	global_store_dword v134, v94, s[0:1] offset:2560
	global_store_dword v134, v78, s[0:1] offset:2688
	v_add_f32_e32 v95, v95, v138
	v_add_f32_e32 v79, v79, v139
	v_mul_f32_e32 v128, 0xbfb8aa3b, v95
	v_mul_f32_e32 v133, 0xbfb8aa3b, v79
	v_exp_f32_e64 v128, -|v128|
	v_exp_f32_e64 v133, -|v133|
	v_max_f32_e32 v95, 0, v95
	v_max_f32_e32 v79, 0, v79
	v_fma_f32 v131, v128, s101, 0.5
	v_fma_f32 v136, v133, s101, 0.5
	v_cmp_le_f32_e32 vcc, s100, v128
	v_cmp_le_f32_e64 s[24:25], s100, v133
	v_fma_f32 v131, -v128, v131, 1.0
	v_fma_f32 v136, -v133, v136, 1.0
	v_add_f32_e32 v132, 1.0, v128
	v_add_f32_e32 v137, 1.0, v133
	v_mul_f32_e32 v131, v128, v131
	v_mul_f32_e32 v136, v133, v136
	v_log_f32_e32 v132, v132
	v_log_f32_e32 v137, v137
	v_mul_f32_e32 v128, 0xbf317217, v132
	v_mul_f32_e32 v133, 0xbf317217, v137
	v_fmac_f32_e32 v128, 0x3f317217, v132
	v_fmac_f32_e32 v133, 0x3f317217, v137
	v_fmac_f32_e32 v128, 0x3377d1cf, v132
	v_fmac_f32_e32 v133, 0x3377d1cf, v137
	v_fmac_f32_e32 v128, 0x3f317217, v132
	v_fmac_f32_e32 v133, 0x3f317217, v137
	v_cndmask_b32_e32 v131, v131, v128, vcc
	v_cndmask_b32_e64 v136, v136, v133, s[24:25]
	v_add_f32_e32 v95, v95, v131
	v_add_f32_e32 v79, v79, v136
	global_store_dword v134, v95, s[0:1] offset:2816
	global_store_dword v134, v79, s[0:1] offset:2944
	s_add_u32 s0, s12, 0x4000
	s_addc_u32 s1, s13, 0
	v_add_f32_e32 v48, v48, v138
	v_add_f32_e32 v32, v32, v139
	v_mul_f32_e32 v128, 0xbfb8aa3b, v48
	v_mul_f32_e32 v133, 0xbfb8aa3b, v32
	v_exp_f32_e64 v128, -|v128|
	v_exp_f32_e64 v133, -|v133|
	v_max_f32_e32 v48, 0, v48
	v_max_f32_e32 v32, 0, v32
	v_fma_f32 v131, v128, s101, 0.5
	v_fma_f32 v136, v133, s101, 0.5
	v_cmp_le_f32_e32 vcc, s100, v128
	v_cmp_le_f32_e64 s[24:25], s100, v133
	v_fma_f32 v131, -v128, v131, 1.0
	v_fma_f32 v136, -v133, v136, 1.0
	v_add_f32_e32 v132, 1.0, v128
	v_add_f32_e32 v137, 1.0, v133
	v_mul_f32_e32 v131, v128, v131
	v_mul_f32_e32 v136, v133, v136
	v_log_f32_e32 v132, v132
	v_log_f32_e32 v137, v137
	v_mul_f32_e32 v128, 0xbf317217, v132
	v_mul_f32_e32 v133, 0xbf317217, v137
	v_fmac_f32_e32 v128, 0x3f317217, v132
	v_fmac_f32_e32 v133, 0x3f317217, v137
	v_fmac_f32_e32 v128, 0x3377d1cf, v132
	v_fmac_f32_e32 v133, 0x3377d1cf, v137
	v_fmac_f32_e32 v128, 0x3f317217, v132
	v_fmac_f32_e32 v133, 0x3f317217, v137
	v_cndmask_b32_e32 v131, v131, v128, vcc
	v_cndmask_b32_e64 v136, v136, v133, s[24:25]
	v_add_f32_e32 v48, v48, v131
	v_add_f32_e32 v32, v32, v136
	global_store_dword v134, v48, s[0:1]
	global_store_dword v134, v32, s[0:1] offset:128
	v_add_f32_e32 v49, v49, v138
	v_add_f32_e32 v33, v33, v139
	v_mul_f32_e32 v128, 0xbfb8aa3b, v49
	v_mul_f32_e32 v133, 0xbfb8aa3b, v33
	v_exp_f32_e64 v128, -|v128|
	v_exp_f32_e64 v133, -|v133|
	v_max_f32_e32 v49, 0, v49
	v_max_f32_e32 v33, 0, v33
	v_fma_f32 v131, v128, s101, 0.5
	v_fma_f32 v136, v133, s101, 0.5
	v_cmp_le_f32_e32 vcc, s100, v128
	v_cmp_le_f32_e64 s[24:25], s100, v133
	v_fma_f32 v131, -v128, v131, 1.0
	v_fma_f32 v136, -v133, v136, 1.0
	v_add_f32_e32 v132, 1.0, v128
	v_add_f32_e32 v137, 1.0, v133
	v_mul_f32_e32 v131, v128, v131
	v_mul_f32_e32 v136, v133, v136
	v_log_f32_e32 v132, v132
	v_log_f32_e32 v137, v137
	v_mul_f32_e32 v128, 0xbf317217, v132
	v_mul_f32_e32 v133, 0xbf317217, v137
	v_fmac_f32_e32 v128, 0x3f317217, v132
	v_fmac_f32_e32 v133, 0x3f317217, v137
	v_fmac_f32_e32 v128, 0x3377d1cf, v132
	v_fmac_f32_e32 v133, 0x3377d1cf, v137
	v_fmac_f32_e32 v128, 0x3f317217, v132
	v_fmac_f32_e32 v133, 0x3f317217, v137
	v_cndmask_b32_e32 v131, v131, v128, vcc
	v_cndmask_b32_e64 v136, v136, v133, s[24:25]
	v_add_f32_e32 v49, v49, v131
	v_add_f32_e32 v33, v33, v136
	global_store_dword v134, v49, s[0:1] offset:256
	global_store_dword v134, v33, s[0:1] offset:384
	v_add_f32_e32 v50, v50, v138
	v_add_f32_e32 v34, v34, v139
	v_mul_f32_e32 v128, 0xbfb8aa3b, v50
	v_mul_f32_e32 v133, 0xbfb8aa3b, v34
	v_exp_f32_e64 v128, -|v128|
	v_exp_f32_e64 v133, -|v133|
	v_max_f32_e32 v50, 0, v50
	v_max_f32_e32 v34, 0, v34
	v_fma_f32 v131, v128, s101, 0.5
	v_fma_f32 v136, v133, s101, 0.5
	v_cmp_le_f32_e32 vcc, s100, v128
	v_cmp_le_f32_e64 s[24:25], s100, v133
	v_fma_f32 v131, -v128, v131, 1.0
	v_fma_f32 v136, -v133, v136, 1.0
	v_add_f32_e32 v132, 1.0, v128
	v_add_f32_e32 v137, 1.0, v133
	v_mul_f32_e32 v131, v128, v131
	v_mul_f32_e32 v136, v133, v136
	v_log_f32_e32 v132, v132
	v_log_f32_e32 v137, v137
	v_mul_f32_e32 v128, 0xbf317217, v132
	v_mul_f32_e32 v133, 0xbf317217, v137
	v_fmac_f32_e32 v128, 0x3f317217, v132
	v_fmac_f32_e32 v133, 0x3f317217, v137
	v_fmac_f32_e32 v128, 0x3377d1cf, v132
	v_fmac_f32_e32 v133, 0x3377d1cf, v137
	v_fmac_f32_e32 v128, 0x3f317217, v132
	v_fmac_f32_e32 v133, 0x3f317217, v137
	v_cndmask_b32_e32 v131, v131, v128, vcc
	v_cndmask_b32_e64 v136, v136, v133, s[24:25]
	v_add_f32_e32 v50, v50, v131
	v_add_f32_e32 v34, v34, v136
	global_store_dword v134, v50, s[0:1] offset:512
	global_store_dword v134, v34, s[0:1] offset:640
	v_add_f32_e32 v51, v51, v138
	v_add_f32_e32 v35, v35, v139
	v_mul_f32_e32 v128, 0xbfb8aa3b, v51
	v_mul_f32_e32 v133, 0xbfb8aa3b, v35
	v_exp_f32_e64 v128, -|v128|
	v_exp_f32_e64 v133, -|v133|
	v_max_f32_e32 v51, 0, v51
	v_max_f32_e32 v35, 0, v35
	v_fma_f32 v131, v128, s101, 0.5
	v_fma_f32 v136, v133, s101, 0.5
	v_cmp_le_f32_e32 vcc, s100, v128
	v_cmp_le_f32_e64 s[24:25], s100, v133
	v_fma_f32 v131, -v128, v131, 1.0
	v_fma_f32 v136, -v133, v136, 1.0
	v_add_f32_e32 v132, 1.0, v128
	v_add_f32_e32 v137, 1.0, v133
	v_mul_f32_e32 v131, v128, v131
	v_mul_f32_e32 v136, v133, v136
	v_log_f32_e32 v132, v132
	v_log_f32_e32 v137, v137
	v_mul_f32_e32 v128, 0xbf317217, v132
	v_mul_f32_e32 v133, 0xbf317217, v137
	v_fmac_f32_e32 v128, 0x3f317217, v132
	v_fmac_f32_e32 v133, 0x3f317217, v137
	v_fmac_f32_e32 v128, 0x3377d1cf, v132
	v_fmac_f32_e32 v133, 0x3377d1cf, v137
	v_fmac_f32_e32 v128, 0x3f317217, v132
	v_fmac_f32_e32 v133, 0x3f317217, v137
	v_cndmask_b32_e32 v131, v131, v128, vcc
	v_cndmask_b32_e64 v136, v136, v133, s[24:25]
	v_add_f32_e32 v51, v51, v131
	v_add_f32_e32 v35, v35, v136
	global_store_dword v134, v51, s[0:1] offset:768
	global_store_dword v134, v35, s[0:1] offset:896
	v_add_f32_e32 v52, v52, v138
	v_add_f32_e32 v36, v36, v139
	v_mul_f32_e32 v128, 0xbfb8aa3b, v52
	v_mul_f32_e32 v133, 0xbfb8aa3b, v36
	v_exp_f32_e64 v128, -|v128|
	v_exp_f32_e64 v133, -|v133|
	v_max_f32_e32 v52, 0, v52
	v_max_f32_e32 v36, 0, v36
	v_fma_f32 v131, v128, s101, 0.5
	v_fma_f32 v136, v133, s101, 0.5
	v_cmp_le_f32_e32 vcc, s100, v128
	v_cmp_le_f32_e64 s[24:25], s100, v133
	v_fma_f32 v131, -v128, v131, 1.0
	v_fma_f32 v136, -v133, v136, 1.0
	v_add_f32_e32 v132, 1.0, v128
	v_add_f32_e32 v137, 1.0, v133
	v_mul_f32_e32 v131, v128, v131
	v_mul_f32_e32 v136, v133, v136
	v_log_f32_e32 v132, v132
	v_log_f32_e32 v137, v137
	v_mul_f32_e32 v128, 0xbf317217, v132
	v_mul_f32_e32 v133, 0xbf317217, v137
	v_fmac_f32_e32 v128, 0x3f317217, v132
	v_fmac_f32_e32 v133, 0x3f317217, v137
	v_fmac_f32_e32 v128, 0x3377d1cf, v132
	v_fmac_f32_e32 v133, 0x3377d1cf, v137
	v_fmac_f32_e32 v128, 0x3f317217, v132
	v_fmac_f32_e32 v133, 0x3f317217, v137
	v_cndmask_b32_e32 v131, v131, v128, vcc
	v_cndmask_b32_e64 v136, v136, v133, s[24:25]
	v_add_f32_e32 v52, v52, v131
	v_add_f32_e32 v36, v36, v136
	global_store_dword v134, v52, s[0:1] offset:2048
	global_store_dword v134, v36, s[0:1] offset:2176
	v_add_f32_e32 v53, v53, v138
	v_add_f32_e32 v37, v37, v139
	v_mul_f32_e32 v128, 0xbfb8aa3b, v53
	v_mul_f32_e32 v133, 0xbfb8aa3b, v37
	v_exp_f32_e64 v128, -|v128|
	v_exp_f32_e64 v133, -|v133|
	v_max_f32_e32 v53, 0, v53
	v_max_f32_e32 v37, 0, v37
	v_fma_f32 v131, v128, s101, 0.5
	v_fma_f32 v136, v133, s101, 0.5
	v_cmp_le_f32_e32 vcc, s100, v128
	v_cmp_le_f32_e64 s[24:25], s100, v133
	v_fma_f32 v131, -v128, v131, 1.0
	v_fma_f32 v136, -v133, v136, 1.0
	v_add_f32_e32 v132, 1.0, v128
	v_add_f32_e32 v137, 1.0, v133
	v_mul_f32_e32 v131, v128, v131
	v_mul_f32_e32 v136, v133, v136
	v_log_f32_e32 v132, v132
	v_log_f32_e32 v137, v137
	v_mul_f32_e32 v128, 0xbf317217, v132
	v_mul_f32_e32 v133, 0xbf317217, v137
	v_fmac_f32_e32 v128, 0x3f317217, v132
	v_fmac_f32_e32 v133, 0x3f317217, v137
	v_fmac_f32_e32 v128, 0x3377d1cf, v132
	v_fmac_f32_e32 v133, 0x3377d1cf, v137
	v_fmac_f32_e32 v128, 0x3f317217, v132
	v_fmac_f32_e32 v133, 0x3f317217, v137
	v_cndmask_b32_e32 v131, v131, v128, vcc
	v_cndmask_b32_e64 v136, v136, v133, s[24:25]
	v_add_f32_e32 v53, v53, v131
	v_add_f32_e32 v37, v37, v136
	global_store_dword v134, v53, s[0:1] offset:2304
	global_store_dword v134, v37, s[0:1] offset:2432
	v_add_f32_e32 v54, v54, v138
	v_add_f32_e32 v38, v38, v139
	v_mul_f32_e32 v128, 0xbfb8aa3b, v54
	v_mul_f32_e32 v133, 0xbfb8aa3b, v38
	v_exp_f32_e64 v128, -|v128|
	v_exp_f32_e64 v133, -|v133|
	v_max_f32_e32 v54, 0, v54
	v_max_f32_e32 v38, 0, v38
	v_fma_f32 v131, v128, s101, 0.5
	v_fma_f32 v136, v133, s101, 0.5
	v_cmp_le_f32_e32 vcc, s100, v128
	v_cmp_le_f32_e64 s[24:25], s100, v133
	v_fma_f32 v131, -v128, v131, 1.0
	v_fma_f32 v136, -v133, v136, 1.0
	v_add_f32_e32 v132, 1.0, v128
	v_add_f32_e32 v137, 1.0, v133
	v_mul_f32_e32 v131, v128, v131
	v_mul_f32_e32 v136, v133, v136
	v_log_f32_e32 v132, v132
	v_log_f32_e32 v137, v137
	v_mul_f32_e32 v128, 0xbf317217, v132
	v_mul_f32_e32 v133, 0xbf317217, v137
	v_fmac_f32_e32 v128, 0x3f317217, v132
	v_fmac_f32_e32 v133, 0x3f317217, v137
	v_fmac_f32_e32 v128, 0x3377d1cf, v132
	v_fmac_f32_e32 v133, 0x3377d1cf, v137
	v_fmac_f32_e32 v128, 0x3f317217, v132
	v_fmac_f32_e32 v133, 0x3f317217, v137
	v_cndmask_b32_e32 v131, v131, v128, vcc
	v_cndmask_b32_e64 v136, v136, v133, s[24:25]
	v_add_f32_e32 v54, v54, v131
	v_add_f32_e32 v38, v38, v136
	global_store_dword v134, v54, s[0:1] offset:2560
	global_store_dword v134, v38, s[0:1] offset:2688
	v_add_f32_e32 v55, v55, v138
	v_add_f32_e32 v39, v39, v139
	v_mul_f32_e32 v128, 0xbfb8aa3b, v55
	v_mul_f32_e32 v133, 0xbfb8aa3b, v39
	v_exp_f32_e64 v128, -|v128|
	v_exp_f32_e64 v133, -|v133|
	v_max_f32_e32 v55, 0, v55
	v_max_f32_e32 v39, 0, v39
	v_fma_f32 v131, v128, s101, 0.5
	v_fma_f32 v136, v133, s101, 0.5
	v_cmp_le_f32_e32 vcc, s100, v128
	v_cmp_le_f32_e64 s[24:25], s100, v133
	v_fma_f32 v131, -v128, v131, 1.0
	v_fma_f32 v136, -v133, v136, 1.0
	v_add_f32_e32 v132, 1.0, v128
	v_add_f32_e32 v137, 1.0, v133
	v_mul_f32_e32 v131, v128, v131
	v_mul_f32_e32 v136, v133, v136
	v_log_f32_e32 v132, v132
	v_log_f32_e32 v137, v137
	v_mul_f32_e32 v128, 0xbf317217, v132
	v_mul_f32_e32 v133, 0xbf317217, v137
	v_fmac_f32_e32 v128, 0x3f317217, v132
	v_fmac_f32_e32 v133, 0x3f317217, v137
	v_fmac_f32_e32 v128, 0x3377d1cf, v132
	v_fmac_f32_e32 v133, 0x3377d1cf, v137
	v_fmac_f32_e32 v128, 0x3f317217, v132
	v_fmac_f32_e32 v133, 0x3f317217, v137
	v_cndmask_b32_e32 v131, v131, v128, vcc
	v_cndmask_b32_e64 v136, v136, v133, s[24:25]
	v_add_f32_e32 v55, v55, v131
	v_add_f32_e32 v39, v39, v136
	global_store_dword v134, v55, s[0:1] offset:2816
	global_store_dword v134, v39, s[0:1] offset:2944
	s_add_u32 s0, s12, 0x5000
	s_addc_u32 s1, s13, 0
	v_add_f32_e32 v56, v56, v138
	v_add_f32_e32 v40, v40, v139
	v_mul_f32_e32 v128, 0xbfb8aa3b, v56
	v_mul_f32_e32 v133, 0xbfb8aa3b, v40
	v_exp_f32_e64 v128, -|v128|
	v_exp_f32_e64 v133, -|v133|
	v_max_f32_e32 v56, 0, v56
	v_max_f32_e32 v40, 0, v40
	v_fma_f32 v131, v128, s101, 0.5
	v_fma_f32 v136, v133, s101, 0.5
	v_cmp_le_f32_e32 vcc, s100, v128
	v_cmp_le_f32_e64 s[24:25], s100, v133
	v_fma_f32 v131, -v128, v131, 1.0
	v_fma_f32 v136, -v133, v136, 1.0
	v_add_f32_e32 v132, 1.0, v128
	v_add_f32_e32 v137, 1.0, v133
	v_mul_f32_e32 v131, v128, v131
	v_mul_f32_e32 v136, v133, v136
	v_log_f32_e32 v132, v132
	v_log_f32_e32 v137, v137
	v_mul_f32_e32 v128, 0xbf317217, v132
	v_mul_f32_e32 v133, 0xbf317217, v137
	v_fmac_f32_e32 v128, 0x3f317217, v132
	v_fmac_f32_e32 v133, 0x3f317217, v137
	v_fmac_f32_e32 v128, 0x3377d1cf, v132
	v_fmac_f32_e32 v133, 0x3377d1cf, v137
	v_fmac_f32_e32 v128, 0x3f317217, v132
	v_fmac_f32_e32 v133, 0x3f317217, v137
	v_cndmask_b32_e32 v131, v131, v128, vcc
	v_cndmask_b32_e64 v136, v136, v133, s[24:25]
	v_add_f32_e32 v56, v56, v131
	v_add_f32_e32 v40, v40, v136
	global_store_dword v134, v56, s[0:1]
	global_store_dword v134, v40, s[0:1] offset:128
	v_add_f32_e32 v57, v57, v138
	v_add_f32_e32 v41, v41, v139
	v_mul_f32_e32 v128, 0xbfb8aa3b, v57
	v_mul_f32_e32 v133, 0xbfb8aa3b, v41
	v_exp_f32_e64 v128, -|v128|
	v_exp_f32_e64 v133, -|v133|
	v_max_f32_e32 v57, 0, v57
	v_max_f32_e32 v41, 0, v41
	v_fma_f32 v131, v128, s101, 0.5
	v_fma_f32 v136, v133, s101, 0.5
	v_cmp_le_f32_e32 vcc, s100, v128
	v_cmp_le_f32_e64 s[24:25], s100, v133
	v_fma_f32 v131, -v128, v131, 1.0
	v_fma_f32 v136, -v133, v136, 1.0
	v_add_f32_e32 v132, 1.0, v128
	v_add_f32_e32 v137, 1.0, v133
	v_mul_f32_e32 v131, v128, v131
	v_mul_f32_e32 v136, v133, v136
	v_log_f32_e32 v132, v132
	v_log_f32_e32 v137, v137
	v_mul_f32_e32 v128, 0xbf317217, v132
	v_mul_f32_e32 v133, 0xbf317217, v137
	v_fmac_f32_e32 v128, 0x3f317217, v132
	v_fmac_f32_e32 v133, 0x3f317217, v137
	v_fmac_f32_e32 v128, 0x3377d1cf, v132
	v_fmac_f32_e32 v133, 0x3377d1cf, v137
	v_fmac_f32_e32 v128, 0x3f317217, v132
	v_fmac_f32_e32 v133, 0x3f317217, v137
	v_cndmask_b32_e32 v131, v131, v128, vcc
	v_cndmask_b32_e64 v136, v136, v133, s[24:25]
	v_add_f32_e32 v57, v57, v131
	v_add_f32_e32 v41, v41, v136
	global_store_dword v134, v57, s[0:1] offset:256
	global_store_dword v134, v41, s[0:1] offset:384
	v_add_f32_e32 v58, v58, v138
	v_add_f32_e32 v42, v42, v139
	v_mul_f32_e32 v128, 0xbfb8aa3b, v58
	v_mul_f32_e32 v133, 0xbfb8aa3b, v42
	v_exp_f32_e64 v128, -|v128|
	v_exp_f32_e64 v133, -|v133|
	v_max_f32_e32 v58, 0, v58
	v_max_f32_e32 v42, 0, v42
	v_fma_f32 v131, v128, s101, 0.5
	v_fma_f32 v136, v133, s101, 0.5
	v_cmp_le_f32_e32 vcc, s100, v128
	v_cmp_le_f32_e64 s[24:25], s100, v133
	v_fma_f32 v131, -v128, v131, 1.0
	v_fma_f32 v136, -v133, v136, 1.0
	v_add_f32_e32 v132, 1.0, v128
	v_add_f32_e32 v137, 1.0, v133
	v_mul_f32_e32 v131, v128, v131
	v_mul_f32_e32 v136, v133, v136
	v_log_f32_e32 v132, v132
	v_log_f32_e32 v137, v137
	v_mul_f32_e32 v128, 0xbf317217, v132
	v_mul_f32_e32 v133, 0xbf317217, v137
	v_fmac_f32_e32 v128, 0x3f317217, v132
	v_fmac_f32_e32 v133, 0x3f317217, v137
	v_fmac_f32_e32 v128, 0x3377d1cf, v132
	v_fmac_f32_e32 v133, 0x3377d1cf, v137
	v_fmac_f32_e32 v128, 0x3f317217, v132
	v_fmac_f32_e32 v133, 0x3f317217, v137
	v_cndmask_b32_e32 v131, v131, v128, vcc
	v_cndmask_b32_e64 v136, v136, v133, s[24:25]
	v_add_f32_e32 v58, v58, v131
	v_add_f32_e32 v42, v42, v136
	global_store_dword v134, v58, s[0:1] offset:512
	global_store_dword v134, v42, s[0:1] offset:640
	v_add_f32_e32 v59, v59, v138
	v_add_f32_e32 v43, v43, v139
	v_mul_f32_e32 v128, 0xbfb8aa3b, v59
	v_mul_f32_e32 v133, 0xbfb8aa3b, v43
	v_exp_f32_e64 v128, -|v128|
	v_exp_f32_e64 v133, -|v133|
	v_max_f32_e32 v59, 0, v59
	v_max_f32_e32 v43, 0, v43
	v_fma_f32 v131, v128, s101, 0.5
	v_fma_f32 v136, v133, s101, 0.5
	v_cmp_le_f32_e32 vcc, s100, v128
	v_cmp_le_f32_e64 s[24:25], s100, v133
	v_fma_f32 v131, -v128, v131, 1.0
	v_fma_f32 v136, -v133, v136, 1.0
	v_add_f32_e32 v132, 1.0, v128
	v_add_f32_e32 v137, 1.0, v133
	v_mul_f32_e32 v131, v128, v131
	v_mul_f32_e32 v136, v133, v136
	v_log_f32_e32 v132, v132
	v_log_f32_e32 v137, v137
	v_mul_f32_e32 v128, 0xbf317217, v132
	v_mul_f32_e32 v133, 0xbf317217, v137
	v_fmac_f32_e32 v128, 0x3f317217, v132
	v_fmac_f32_e32 v133, 0x3f317217, v137
	v_fmac_f32_e32 v128, 0x3377d1cf, v132
	v_fmac_f32_e32 v133, 0x3377d1cf, v137
	v_fmac_f32_e32 v128, 0x3f317217, v132
	v_fmac_f32_e32 v133, 0x3f317217, v137
	v_cndmask_b32_e32 v131, v131, v128, vcc
	v_cndmask_b32_e64 v136, v136, v133, s[24:25]
	v_add_f32_e32 v59, v59, v131
	v_add_f32_e32 v43, v43, v136
	global_store_dword v134, v59, s[0:1] offset:768
	global_store_dword v134, v43, s[0:1] offset:896
	v_add_f32_e32 v60, v60, v138
	v_add_f32_e32 v44, v44, v139
	v_mul_f32_e32 v128, 0xbfb8aa3b, v60
	v_mul_f32_e32 v133, 0xbfb8aa3b, v44
	v_exp_f32_e64 v128, -|v128|
	v_exp_f32_e64 v133, -|v133|
	v_max_f32_e32 v60, 0, v60
	v_max_f32_e32 v44, 0, v44
	v_fma_f32 v131, v128, s101, 0.5
	v_fma_f32 v136, v133, s101, 0.5
	v_cmp_le_f32_e32 vcc, s100, v128
	v_cmp_le_f32_e64 s[24:25], s100, v133
	v_fma_f32 v131, -v128, v131, 1.0
	v_fma_f32 v136, -v133, v136, 1.0
	v_add_f32_e32 v132, 1.0, v128
	v_add_f32_e32 v137, 1.0, v133
	v_mul_f32_e32 v131, v128, v131
	v_mul_f32_e32 v136, v133, v136
	v_log_f32_e32 v132, v132
	v_log_f32_e32 v137, v137
	v_mul_f32_e32 v128, 0xbf317217, v132
	v_mul_f32_e32 v133, 0xbf317217, v137
	v_fmac_f32_e32 v128, 0x3f317217, v132
	v_fmac_f32_e32 v133, 0x3f317217, v137
	v_fmac_f32_e32 v128, 0x3377d1cf, v132
	v_fmac_f32_e32 v133, 0x3377d1cf, v137
	v_fmac_f32_e32 v128, 0x3f317217, v132
	v_fmac_f32_e32 v133, 0x3f317217, v137
	v_cndmask_b32_e32 v131, v131, v128, vcc
	v_cndmask_b32_e64 v136, v136, v133, s[24:25]
	v_add_f32_e32 v60, v60, v131
	v_add_f32_e32 v44, v44, v136
	global_store_dword v134, v60, s[0:1] offset:2048
	global_store_dword v134, v44, s[0:1] offset:2176
	v_add_f32_e32 v61, v61, v138
	v_add_f32_e32 v45, v45, v139
	v_mul_f32_e32 v128, 0xbfb8aa3b, v61
	v_mul_f32_e32 v133, 0xbfb8aa3b, v45
	v_exp_f32_e64 v128, -|v128|
	v_exp_f32_e64 v133, -|v133|
	v_max_f32_e32 v61, 0, v61
	v_max_f32_e32 v45, 0, v45
	v_fma_f32 v131, v128, s101, 0.5
	v_fma_f32 v136, v133, s101, 0.5
	v_cmp_le_f32_e32 vcc, s100, v128
	v_cmp_le_f32_e64 s[24:25], s100, v133
	v_fma_f32 v131, -v128, v131, 1.0
	v_fma_f32 v136, -v133, v136, 1.0
	v_add_f32_e32 v132, 1.0, v128
	v_add_f32_e32 v137, 1.0, v133
	v_mul_f32_e32 v131, v128, v131
	v_mul_f32_e32 v136, v133, v136
	v_log_f32_e32 v132, v132
	v_log_f32_e32 v137, v137
	v_mul_f32_e32 v128, 0xbf317217, v132
	v_mul_f32_e32 v133, 0xbf317217, v137
	v_fmac_f32_e32 v128, 0x3f317217, v132
	v_fmac_f32_e32 v133, 0x3f317217, v137
	v_fmac_f32_e32 v128, 0x3377d1cf, v132
	v_fmac_f32_e32 v133, 0x3377d1cf, v137
	v_fmac_f32_e32 v128, 0x3f317217, v132
	v_fmac_f32_e32 v133, 0x3f317217, v137
	v_cndmask_b32_e32 v131, v131, v128, vcc
	v_cndmask_b32_e64 v136, v136, v133, s[24:25]
	v_add_f32_e32 v61, v61, v131
	v_add_f32_e32 v45, v45, v136
	global_store_dword v134, v61, s[0:1] offset:2304
	global_store_dword v134, v45, s[0:1] offset:2432
	v_add_f32_e32 v62, v62, v138
	v_add_f32_e32 v46, v46, v139
	v_mul_f32_e32 v128, 0xbfb8aa3b, v62
	v_mul_f32_e32 v133, 0xbfb8aa3b, v46
	v_exp_f32_e64 v128, -|v128|
	v_exp_f32_e64 v133, -|v133|
	v_max_f32_e32 v62, 0, v62
	v_max_f32_e32 v46, 0, v46
	v_fma_f32 v131, v128, s101, 0.5
	v_fma_f32 v136, v133, s101, 0.5
	v_cmp_le_f32_e32 vcc, s100, v128
	v_cmp_le_f32_e64 s[24:25], s100, v133
	v_fma_f32 v131, -v128, v131, 1.0
	v_fma_f32 v136, -v133, v136, 1.0
	v_add_f32_e32 v132, 1.0, v128
	v_add_f32_e32 v137, 1.0, v133
	v_mul_f32_e32 v131, v128, v131
	v_mul_f32_e32 v136, v133, v136
	v_log_f32_e32 v132, v132
	v_log_f32_e32 v137, v137
	v_mul_f32_e32 v128, 0xbf317217, v132
	v_mul_f32_e32 v133, 0xbf317217, v137
	v_fmac_f32_e32 v128, 0x3f317217, v132
	v_fmac_f32_e32 v133, 0x3f317217, v137
	v_fmac_f32_e32 v128, 0x3377d1cf, v132
	v_fmac_f32_e32 v133, 0x3377d1cf, v137
	v_fmac_f32_e32 v128, 0x3f317217, v132
	v_fmac_f32_e32 v133, 0x3f317217, v137
	v_cndmask_b32_e32 v131, v131, v128, vcc
	v_cndmask_b32_e64 v136, v136, v133, s[24:25]
	v_add_f32_e32 v62, v62, v131
	v_add_f32_e32 v46, v46, v136
	global_store_dword v134, v62, s[0:1] offset:2560
	global_store_dword v134, v46, s[0:1] offset:2688
	v_add_f32_e32 v63, v63, v138
	v_add_f32_e32 v47, v47, v139
	v_mul_f32_e32 v128, 0xbfb8aa3b, v63
	v_mul_f32_e32 v133, 0xbfb8aa3b, v47
	v_exp_f32_e64 v128, -|v128|
	v_exp_f32_e64 v133, -|v133|
	v_max_f32_e32 v63, 0, v63
	v_max_f32_e32 v47, 0, v47
	v_fma_f32 v131, v128, s101, 0.5
	v_fma_f32 v136, v133, s101, 0.5
	v_cmp_le_f32_e32 vcc, s100, v128
	v_cmp_le_f32_e64 s[24:25], s100, v133
	v_fma_f32 v131, -v128, v131, 1.0
	v_fma_f32 v136, -v133, v136, 1.0
	v_add_f32_e32 v132, 1.0, v128
	v_add_f32_e32 v137, 1.0, v133
	v_mul_f32_e32 v131, v128, v131
	v_mul_f32_e32 v136, v133, v136
	v_log_f32_e32 v132, v132
	v_log_f32_e32 v137, v137
	v_mul_f32_e32 v128, 0xbf317217, v132
	v_mul_f32_e32 v133, 0xbf317217, v137
	v_fmac_f32_e32 v128, 0x3f317217, v132
	v_fmac_f32_e32 v133, 0x3f317217, v137
	v_fmac_f32_e32 v128, 0x3377d1cf, v132
	v_fmac_f32_e32 v133, 0x3377d1cf, v137
	v_fmac_f32_e32 v128, 0x3f317217, v132
	v_fmac_f32_e32 v133, 0x3f317217, v137
	v_cndmask_b32_e32 v131, v131, v128, vcc
	v_cndmask_b32_e64 v136, v136, v133, s[24:25]
	v_add_f32_e32 v63, v63, v131
	v_add_f32_e32 v47, v47, v136
	global_store_dword v134, v63, s[0:1] offset:2816
	global_store_dword v134, v47, s[0:1] offset:2944
	s_add_u32 s0, s12, 0x6000
	s_addc_u32 s1, s13, 0
	v_add_f32_e32 v16, v16, v138
	v_add_f32_e32 v0, v0, v139
	v_mul_f32_e32 v128, 0xbfb8aa3b, v16
	v_mul_f32_e32 v133, 0xbfb8aa3b, v0
	v_exp_f32_e64 v128, -|v128|
	v_exp_f32_e64 v133, -|v133|
	v_max_f32_e32 v16, 0, v16
	v_max_f32_e32 v0, 0, v0
	v_fma_f32 v131, v128, s101, 0.5
	v_fma_f32 v136, v133, s101, 0.5
	v_cmp_le_f32_e32 vcc, s100, v128
	v_cmp_le_f32_e64 s[24:25], s100, v133
	v_fma_f32 v131, -v128, v131, 1.0
	v_fma_f32 v136, -v133, v136, 1.0
	v_add_f32_e32 v132, 1.0, v128
	v_add_f32_e32 v137, 1.0, v133
	v_mul_f32_e32 v131, v128, v131
	v_mul_f32_e32 v136, v133, v136
	v_log_f32_e32 v132, v132
	v_log_f32_e32 v137, v137
	v_mul_f32_e32 v128, 0xbf317217, v132
	v_mul_f32_e32 v133, 0xbf317217, v137
	v_fmac_f32_e32 v128, 0x3f317217, v132
	v_fmac_f32_e32 v133, 0x3f317217, v137
	v_fmac_f32_e32 v128, 0x3377d1cf, v132
	v_fmac_f32_e32 v133, 0x3377d1cf, v137
	v_fmac_f32_e32 v128, 0x3f317217, v132
	v_fmac_f32_e32 v133, 0x3f317217, v137
	v_cndmask_b32_e32 v131, v131, v128, vcc
	v_cndmask_b32_e64 v136, v136, v133, s[24:25]
	v_add_f32_e32 v16, v16, v131
	v_add_f32_e32 v0, v0, v136
	global_store_dword v134, v16, s[0:1]
	global_store_dword v134, v0, s[0:1] offset:128
	v_add_f32_e32 v17, v17, v138
	v_add_f32_e32 v1, v1, v139
	v_mul_f32_e32 v128, 0xbfb8aa3b, v17
	v_mul_f32_e32 v133, 0xbfb8aa3b, v1
	v_exp_f32_e64 v128, -|v128|
	v_exp_f32_e64 v133, -|v133|
	v_max_f32_e32 v17, 0, v17
	v_max_f32_e32 v1, 0, v1
	v_fma_f32 v131, v128, s101, 0.5
	v_fma_f32 v136, v133, s101, 0.5
	v_cmp_le_f32_e32 vcc, s100, v128
	v_cmp_le_f32_e64 s[24:25], s100, v133
	v_fma_f32 v131, -v128, v131, 1.0
	v_fma_f32 v136, -v133, v136, 1.0
	v_add_f32_e32 v132, 1.0, v128
	v_add_f32_e32 v137, 1.0, v133
	v_mul_f32_e32 v131, v128, v131
	v_mul_f32_e32 v136, v133, v136
	v_log_f32_e32 v132, v132
	v_log_f32_e32 v137, v137
	v_mul_f32_e32 v128, 0xbf317217, v132
	v_mul_f32_e32 v133, 0xbf317217, v137
	v_fmac_f32_e32 v128, 0x3f317217, v132
	v_fmac_f32_e32 v133, 0x3f317217, v137
	v_fmac_f32_e32 v128, 0x3377d1cf, v132
	v_fmac_f32_e32 v133, 0x3377d1cf, v137
	v_fmac_f32_e32 v128, 0x3f317217, v132
	v_fmac_f32_e32 v133, 0x3f317217, v137
	v_cndmask_b32_e32 v131, v131, v128, vcc
	v_cndmask_b32_e64 v136, v136, v133, s[24:25]
	v_add_f32_e32 v17, v17, v131
	v_add_f32_e32 v1, v1, v136
	global_store_dword v134, v17, s[0:1] offset:256
	global_store_dword v134, v1, s[0:1] offset:384
	v_add_f32_e32 v18, v18, v138
	v_add_f32_e32 v2, v2, v139
	v_mul_f32_e32 v128, 0xbfb8aa3b, v18
	v_mul_f32_e32 v133, 0xbfb8aa3b, v2
	v_exp_f32_e64 v128, -|v128|
	v_exp_f32_e64 v133, -|v133|
	v_max_f32_e32 v18, 0, v18
	v_max_f32_e32 v2, 0, v2
	v_fma_f32 v131, v128, s101, 0.5
	v_fma_f32 v136, v133, s101, 0.5
	v_cmp_le_f32_e32 vcc, s100, v128
	v_cmp_le_f32_e64 s[24:25], s100, v133
	v_fma_f32 v131, -v128, v131, 1.0
	v_fma_f32 v136, -v133, v136, 1.0
	v_add_f32_e32 v132, 1.0, v128
	v_add_f32_e32 v137, 1.0, v133
	v_mul_f32_e32 v131, v128, v131
	v_mul_f32_e32 v136, v133, v136
	v_log_f32_e32 v132, v132
	v_log_f32_e32 v137, v137
	v_mul_f32_e32 v128, 0xbf317217, v132
	v_mul_f32_e32 v133, 0xbf317217, v137
	v_fmac_f32_e32 v128, 0x3f317217, v132
	v_fmac_f32_e32 v133, 0x3f317217, v137
	v_fmac_f32_e32 v128, 0x3377d1cf, v132
	v_fmac_f32_e32 v133, 0x3377d1cf, v137
	v_fmac_f32_e32 v128, 0x3f317217, v132
	v_fmac_f32_e32 v133, 0x3f317217, v137
	v_cndmask_b32_e32 v131, v131, v128, vcc
	v_cndmask_b32_e64 v136, v136, v133, s[24:25]
	v_add_f32_e32 v18, v18, v131
	v_add_f32_e32 v2, v2, v136
	global_store_dword v134, v18, s[0:1] offset:512
	global_store_dword v134, v2, s[0:1] offset:640
	v_add_f32_e32 v19, v19, v138
	v_add_f32_e32 v3, v3, v139
	v_mul_f32_e32 v128, 0xbfb8aa3b, v19
	v_mul_f32_e32 v133, 0xbfb8aa3b, v3
	v_exp_f32_e64 v128, -|v128|
	v_exp_f32_e64 v133, -|v133|
	v_max_f32_e32 v19, 0, v19
	v_max_f32_e32 v3, 0, v3
	v_fma_f32 v131, v128, s101, 0.5
	v_fma_f32 v136, v133, s101, 0.5
	v_cmp_le_f32_e32 vcc, s100, v128
	v_cmp_le_f32_e64 s[24:25], s100, v133
	v_fma_f32 v131, -v128, v131, 1.0
	v_fma_f32 v136, -v133, v136, 1.0
	v_add_f32_e32 v132, 1.0, v128
	v_add_f32_e32 v137, 1.0, v133
	v_mul_f32_e32 v131, v128, v131
	v_mul_f32_e32 v136, v133, v136
	v_log_f32_e32 v132, v132
	v_log_f32_e32 v137, v137
	v_mul_f32_e32 v128, 0xbf317217, v132
	v_mul_f32_e32 v133, 0xbf317217, v137
	v_fmac_f32_e32 v128, 0x3f317217, v132
	v_fmac_f32_e32 v133, 0x3f317217, v137
	v_fmac_f32_e32 v128, 0x3377d1cf, v132
	v_fmac_f32_e32 v133, 0x3377d1cf, v137
	v_fmac_f32_e32 v128, 0x3f317217, v132
	v_fmac_f32_e32 v133, 0x3f317217, v137
	v_cndmask_b32_e32 v131, v131, v128, vcc
	v_cndmask_b32_e64 v136, v136, v133, s[24:25]
	v_add_f32_e32 v19, v19, v131
	v_add_f32_e32 v3, v3, v136
	global_store_dword v134, v19, s[0:1] offset:768
	global_store_dword v134, v3, s[0:1] offset:896
	v_add_f32_e32 v20, v20, v138
	v_add_f32_e32 v4, v4, v139
	v_mul_f32_e32 v128, 0xbfb8aa3b, v20
	v_mul_f32_e32 v133, 0xbfb8aa3b, v4
	v_exp_f32_e64 v128, -|v128|
	v_exp_f32_e64 v133, -|v133|
	v_max_f32_e32 v20, 0, v20
	v_max_f32_e32 v4, 0, v4
	v_fma_f32 v131, v128, s101, 0.5
	v_fma_f32 v136, v133, s101, 0.5
	v_cmp_le_f32_e32 vcc, s100, v128
	v_cmp_le_f32_e64 s[24:25], s100, v133
	v_fma_f32 v131, -v128, v131, 1.0
	v_fma_f32 v136, -v133, v136, 1.0
	v_add_f32_e32 v132, 1.0, v128
	v_add_f32_e32 v137, 1.0, v133
	v_mul_f32_e32 v131, v128, v131
	v_mul_f32_e32 v136, v133, v136
	v_log_f32_e32 v132, v132
	v_log_f32_e32 v137, v137
	v_mul_f32_e32 v128, 0xbf317217, v132
	v_mul_f32_e32 v133, 0xbf317217, v137
	v_fmac_f32_e32 v128, 0x3f317217, v132
	v_fmac_f32_e32 v133, 0x3f317217, v137
	v_fmac_f32_e32 v128, 0x3377d1cf, v132
	v_fmac_f32_e32 v133, 0x3377d1cf, v137
	v_fmac_f32_e32 v128, 0x3f317217, v132
	v_fmac_f32_e32 v133, 0x3f317217, v137
	v_cndmask_b32_e32 v131, v131, v128, vcc
	v_cndmask_b32_e64 v136, v136, v133, s[24:25]
	v_add_f32_e32 v20, v20, v131
	v_add_f32_e32 v4, v4, v136
	global_store_dword v134, v20, s[0:1] offset:2048
	global_store_dword v134, v4, s[0:1] offset:2176
	v_add_f32_e32 v21, v21, v138
	v_add_f32_e32 v5, v5, v139
	v_mul_f32_e32 v128, 0xbfb8aa3b, v21
	v_mul_f32_e32 v133, 0xbfb8aa3b, v5
	v_exp_f32_e64 v128, -|v128|
	v_exp_f32_e64 v133, -|v133|
	v_max_f32_e32 v21, 0, v21
	v_max_f32_e32 v5, 0, v5
	v_fma_f32 v131, v128, s101, 0.5
	v_fma_f32 v136, v133, s101, 0.5
	v_cmp_le_f32_e32 vcc, s100, v128
	v_cmp_le_f32_e64 s[24:25], s100, v133
	v_fma_f32 v131, -v128, v131, 1.0
	v_fma_f32 v136, -v133, v136, 1.0
	v_add_f32_e32 v132, 1.0, v128
	v_add_f32_e32 v137, 1.0, v133
	v_mul_f32_e32 v131, v128, v131
	v_mul_f32_e32 v136, v133, v136
	v_log_f32_e32 v132, v132
	v_log_f32_e32 v137, v137
	v_mul_f32_e32 v128, 0xbf317217, v132
	v_mul_f32_e32 v133, 0xbf317217, v137
	v_fmac_f32_e32 v128, 0x3f317217, v132
	v_fmac_f32_e32 v133, 0x3f317217, v137
	v_fmac_f32_e32 v128, 0x3377d1cf, v132
	v_fmac_f32_e32 v133, 0x3377d1cf, v137
	v_fmac_f32_e32 v128, 0x3f317217, v132
	v_fmac_f32_e32 v133, 0x3f317217, v137
	v_cndmask_b32_e32 v131, v131, v128, vcc
	v_cndmask_b32_e64 v136, v136, v133, s[24:25]
	v_add_f32_e32 v21, v21, v131
	v_add_f32_e32 v5, v5, v136
	global_store_dword v134, v21, s[0:1] offset:2304
	global_store_dword v134, v5, s[0:1] offset:2432
	v_add_f32_e32 v22, v22, v138
	v_add_f32_e32 v6, v6, v139
	v_mul_f32_e32 v128, 0xbfb8aa3b, v22
	v_mul_f32_e32 v133, 0xbfb8aa3b, v6
	v_exp_f32_e64 v128, -|v128|
	v_exp_f32_e64 v133, -|v133|
	v_max_f32_e32 v22, 0, v22
	v_max_f32_e32 v6, 0, v6
	v_fma_f32 v131, v128, s101, 0.5
	v_fma_f32 v136, v133, s101, 0.5
	v_cmp_le_f32_e32 vcc, s100, v128
	v_cmp_le_f32_e64 s[24:25], s100, v133
	v_fma_f32 v131, -v128, v131, 1.0
	v_fma_f32 v136, -v133, v136, 1.0
	v_add_f32_e32 v132, 1.0, v128
	v_add_f32_e32 v137, 1.0, v133
	v_mul_f32_e32 v131, v128, v131
	v_mul_f32_e32 v136, v133, v136
	v_log_f32_e32 v132, v132
	v_log_f32_e32 v137, v137
	v_mul_f32_e32 v128, 0xbf317217, v132
	v_mul_f32_e32 v133, 0xbf317217, v137
	v_fmac_f32_e32 v128, 0x3f317217, v132
	v_fmac_f32_e32 v133, 0x3f317217, v137
	v_fmac_f32_e32 v128, 0x3377d1cf, v132
	v_fmac_f32_e32 v133, 0x3377d1cf, v137
	v_fmac_f32_e32 v128, 0x3f317217, v132
	v_fmac_f32_e32 v133, 0x3f317217, v137
	v_cndmask_b32_e32 v131, v131, v128, vcc
	v_cndmask_b32_e64 v136, v136, v133, s[24:25]
	v_add_f32_e32 v22, v22, v131
	v_add_f32_e32 v6, v6, v136
	global_store_dword v134, v22, s[0:1] offset:2560
	global_store_dword v134, v6, s[0:1] offset:2688
	v_add_f32_e32 v23, v23, v138
	v_add_f32_e32 v7, v7, v139
	v_mul_f32_e32 v128, 0xbfb8aa3b, v23
	v_mul_f32_e32 v133, 0xbfb8aa3b, v7
	v_exp_f32_e64 v128, -|v128|
	v_exp_f32_e64 v133, -|v133|
	v_max_f32_e32 v23, 0, v23
	v_max_f32_e32 v7, 0, v7
	v_fma_f32 v131, v128, s101, 0.5
	v_fma_f32 v136, v133, s101, 0.5
	v_cmp_le_f32_e32 vcc, s100, v128
	v_cmp_le_f32_e64 s[24:25], s100, v133
	v_fma_f32 v131, -v128, v131, 1.0
	v_fma_f32 v136, -v133, v136, 1.0
	v_add_f32_e32 v132, 1.0, v128
	v_add_f32_e32 v137, 1.0, v133
	v_mul_f32_e32 v131, v128, v131
	v_mul_f32_e32 v136, v133, v136
	v_log_f32_e32 v132, v132
	v_log_f32_e32 v137, v137
	v_mul_f32_e32 v128, 0xbf317217, v132
	v_mul_f32_e32 v133, 0xbf317217, v137
	v_fmac_f32_e32 v128, 0x3f317217, v132
	v_fmac_f32_e32 v133, 0x3f317217, v137
	v_fmac_f32_e32 v128, 0x3377d1cf, v132
	v_fmac_f32_e32 v133, 0x3377d1cf, v137
	v_fmac_f32_e32 v128, 0x3f317217, v132
	v_fmac_f32_e32 v133, 0x3f317217, v137
	v_cndmask_b32_e32 v131, v131, v128, vcc
	v_cndmask_b32_e64 v136, v136, v133, s[24:25]
	v_add_f32_e32 v23, v23, v131
	v_add_f32_e32 v7, v7, v136
	global_store_dword v134, v23, s[0:1] offset:2816
	global_store_dword v134, v7, s[0:1] offset:2944
	s_add_u32 s0, s12, 0x7000
	s_addc_u32 s1, s13, 0
	v_add_f32_e32 v24, v24, v138
	v_add_f32_e32 v8, v8, v139
	v_mul_f32_e32 v128, 0xbfb8aa3b, v24
	v_mul_f32_e32 v133, 0xbfb8aa3b, v8
	v_exp_f32_e64 v128, -|v128|
	v_exp_f32_e64 v133, -|v133|
	v_max_f32_e32 v24, 0, v24
	v_max_f32_e32 v8, 0, v8
	v_fma_f32 v131, v128, s101, 0.5
	v_fma_f32 v136, v133, s101, 0.5
	v_cmp_le_f32_e32 vcc, s100, v128
	v_cmp_le_f32_e64 s[24:25], s100, v133
	v_fma_f32 v131, -v128, v131, 1.0
	v_fma_f32 v136, -v133, v136, 1.0
	v_add_f32_e32 v132, 1.0, v128
	v_add_f32_e32 v137, 1.0, v133
	v_mul_f32_e32 v131, v128, v131
	v_mul_f32_e32 v136, v133, v136
	v_log_f32_e32 v132, v132
	v_log_f32_e32 v137, v137
	v_mul_f32_e32 v128, 0xbf317217, v132
	v_mul_f32_e32 v133, 0xbf317217, v137
	v_fmac_f32_e32 v128, 0x3f317217, v132
	v_fmac_f32_e32 v133, 0x3f317217, v137
	v_fmac_f32_e32 v128, 0x3377d1cf, v132
	v_fmac_f32_e32 v133, 0x3377d1cf, v137
	v_fmac_f32_e32 v128, 0x3f317217, v132
	v_fmac_f32_e32 v133, 0x3f317217, v137
	v_cndmask_b32_e32 v131, v131, v128, vcc
	v_cndmask_b32_e64 v136, v136, v133, s[24:25]
	v_add_f32_e32 v24, v24, v131
	v_add_f32_e32 v8, v8, v136
	global_store_dword v134, v24, s[0:1]
	global_store_dword v134, v8, s[0:1] offset:128
	v_add_f32_e32 v25, v25, v138
	v_add_f32_e32 v9, v9, v139
	v_mul_f32_e32 v128, 0xbfb8aa3b, v25
	v_mul_f32_e32 v133, 0xbfb8aa3b, v9
	v_exp_f32_e64 v128, -|v128|
	v_exp_f32_e64 v133, -|v133|
	v_max_f32_e32 v25, 0, v25
	v_max_f32_e32 v9, 0, v9
	v_fma_f32 v131, v128, s101, 0.5
	v_fma_f32 v136, v133, s101, 0.5
	v_cmp_le_f32_e32 vcc, s100, v128
	v_cmp_le_f32_e64 s[24:25], s100, v133
	v_fma_f32 v131, -v128, v131, 1.0
	v_fma_f32 v136, -v133, v136, 1.0
	v_add_f32_e32 v132, 1.0, v128
	v_add_f32_e32 v137, 1.0, v133
	v_mul_f32_e32 v131, v128, v131
	v_mul_f32_e32 v136, v133, v136
	v_log_f32_e32 v132, v132
	v_log_f32_e32 v137, v137
	v_mul_f32_e32 v128, 0xbf317217, v132
	v_mul_f32_e32 v133, 0xbf317217, v137
	v_fmac_f32_e32 v128, 0x3f317217, v132
	v_fmac_f32_e32 v133, 0x3f317217, v137
	v_fmac_f32_e32 v128, 0x3377d1cf, v132
	v_fmac_f32_e32 v133, 0x3377d1cf, v137
	v_fmac_f32_e32 v128, 0x3f317217, v132
	v_fmac_f32_e32 v133, 0x3f317217, v137
	v_cndmask_b32_e32 v131, v131, v128, vcc
	v_cndmask_b32_e64 v136, v136, v133, s[24:25]
	v_add_f32_e32 v25, v25, v131
	v_add_f32_e32 v9, v9, v136
	global_store_dword v134, v25, s[0:1] offset:256
	global_store_dword v134, v9, s[0:1] offset:384
	v_add_f32_e32 v26, v26, v138
	v_add_f32_e32 v10, v10, v139
	v_mul_f32_e32 v128, 0xbfb8aa3b, v26
	v_mul_f32_e32 v133, 0xbfb8aa3b, v10
	v_exp_f32_e64 v128, -|v128|
	v_exp_f32_e64 v133, -|v133|
	v_max_f32_e32 v26, 0, v26
	v_max_f32_e32 v10, 0, v10
	v_fma_f32 v131, v128, s101, 0.5
	v_fma_f32 v136, v133, s101, 0.5
	v_cmp_le_f32_e32 vcc, s100, v128
	v_cmp_le_f32_e64 s[24:25], s100, v133
	v_fma_f32 v131, -v128, v131, 1.0
	v_fma_f32 v136, -v133, v136, 1.0
	v_add_f32_e32 v132, 1.0, v128
	v_add_f32_e32 v137, 1.0, v133
	v_mul_f32_e32 v131, v128, v131
	v_mul_f32_e32 v136, v133, v136
	v_log_f32_e32 v132, v132
	v_log_f32_e32 v137, v137
	v_mul_f32_e32 v128, 0xbf317217, v132
	v_mul_f32_e32 v133, 0xbf317217, v137
	v_fmac_f32_e32 v128, 0x3f317217, v132
	v_fmac_f32_e32 v133, 0x3f317217, v137
	v_fmac_f32_e32 v128, 0x3377d1cf, v132
	v_fmac_f32_e32 v133, 0x3377d1cf, v137
	v_fmac_f32_e32 v128, 0x3f317217, v132
	v_fmac_f32_e32 v133, 0x3f317217, v137
	v_cndmask_b32_e32 v131, v131, v128, vcc
	v_cndmask_b32_e64 v136, v136, v133, s[24:25]
	v_add_f32_e32 v26, v26, v131
	v_add_f32_e32 v10, v10, v136
	global_store_dword v134, v26, s[0:1] offset:512
	global_store_dword v134, v10, s[0:1] offset:640
	v_add_f32_e32 v27, v27, v138
	v_add_f32_e32 v11, v11, v139
	v_mul_f32_e32 v128, 0xbfb8aa3b, v27
	v_mul_f32_e32 v133, 0xbfb8aa3b, v11
	v_exp_f32_e64 v128, -|v128|
	v_exp_f32_e64 v133, -|v133|
	v_max_f32_e32 v27, 0, v27
	v_max_f32_e32 v11, 0, v11
	v_fma_f32 v131, v128, s101, 0.5
	v_fma_f32 v136, v133, s101, 0.5
	v_cmp_le_f32_e32 vcc, s100, v128
	v_cmp_le_f32_e64 s[24:25], s100, v133
	v_fma_f32 v131, -v128, v131, 1.0
	v_fma_f32 v136, -v133, v136, 1.0
	v_add_f32_e32 v132, 1.0, v128
	v_add_f32_e32 v137, 1.0, v133
	v_mul_f32_e32 v131, v128, v131
	v_mul_f32_e32 v136, v133, v136
	v_log_f32_e32 v132, v132
	v_log_f32_e32 v137, v137
	v_mul_f32_e32 v128, 0xbf317217, v132
	v_mul_f32_e32 v133, 0xbf317217, v137
	v_fmac_f32_e32 v128, 0x3f317217, v132
	v_fmac_f32_e32 v133, 0x3f317217, v137
	v_fmac_f32_e32 v128, 0x3377d1cf, v132
	v_fmac_f32_e32 v133, 0x3377d1cf, v137
	v_fmac_f32_e32 v128, 0x3f317217, v132
	v_fmac_f32_e32 v133, 0x3f317217, v137
	v_cndmask_b32_e32 v131, v131, v128, vcc
	v_cndmask_b32_e64 v136, v136, v133, s[24:25]
	v_add_f32_e32 v27, v27, v131
	v_add_f32_e32 v11, v11, v136
	global_store_dword v134, v27, s[0:1] offset:768
	global_store_dword v134, v11, s[0:1] offset:896
	v_add_f32_e32 v28, v28, v138
	v_add_f32_e32 v12, v12, v139
	v_mul_f32_e32 v128, 0xbfb8aa3b, v28
	v_mul_f32_e32 v133, 0xbfb8aa3b, v12
	v_exp_f32_e64 v128, -|v128|
	v_exp_f32_e64 v133, -|v133|
	v_max_f32_e32 v28, 0, v28
	v_max_f32_e32 v12, 0, v12
	v_fma_f32 v131, v128, s101, 0.5
	v_fma_f32 v136, v133, s101, 0.5
	v_cmp_le_f32_e32 vcc, s100, v128
	v_cmp_le_f32_e64 s[24:25], s100, v133
	v_fma_f32 v131, -v128, v131, 1.0
	v_fma_f32 v136, -v133, v136, 1.0
	v_add_f32_e32 v132, 1.0, v128
	v_add_f32_e32 v137, 1.0, v133
	v_mul_f32_e32 v131, v128, v131
	v_mul_f32_e32 v136, v133, v136
	v_log_f32_e32 v132, v132
	v_log_f32_e32 v137, v137
	v_mul_f32_e32 v128, 0xbf317217, v132
	v_mul_f32_e32 v133, 0xbf317217, v137
	v_fmac_f32_e32 v128, 0x3f317217, v132
	v_fmac_f32_e32 v133, 0x3f317217, v137
	v_fmac_f32_e32 v128, 0x3377d1cf, v132
	v_fmac_f32_e32 v133, 0x3377d1cf, v137
	v_fmac_f32_e32 v128, 0x3f317217, v132
	v_fmac_f32_e32 v133, 0x3f317217, v137
	v_cndmask_b32_e32 v131, v131, v128, vcc
	v_cndmask_b32_e64 v136, v136, v133, s[24:25]
	v_add_f32_e32 v28, v28, v131
	v_add_f32_e32 v12, v12, v136
	global_store_dword v134, v28, s[0:1] offset:2048
	global_store_dword v134, v12, s[0:1] offset:2176
	v_add_f32_e32 v29, v29, v138
	v_add_f32_e32 v13, v13, v139
	v_mul_f32_e32 v128, 0xbfb8aa3b, v29
	v_mul_f32_e32 v133, 0xbfb8aa3b, v13
	v_exp_f32_e64 v128, -|v128|
	v_exp_f32_e64 v133, -|v133|
	v_max_f32_e32 v29, 0, v29
	v_max_f32_e32 v13, 0, v13
	v_fma_f32 v131, v128, s101, 0.5
	v_fma_f32 v136, v133, s101, 0.5
	v_cmp_le_f32_e32 vcc, s100, v128
	v_cmp_le_f32_e64 s[24:25], s100, v133
	v_fma_f32 v131, -v128, v131, 1.0
	v_fma_f32 v136, -v133, v136, 1.0
	v_add_f32_e32 v132, 1.0, v128
	v_add_f32_e32 v137, 1.0, v133
	v_mul_f32_e32 v131, v128, v131
	v_mul_f32_e32 v136, v133, v136
	v_log_f32_e32 v132, v132
	v_log_f32_e32 v137, v137
	v_mul_f32_e32 v128, 0xbf317217, v132
	v_mul_f32_e32 v133, 0xbf317217, v137
	v_fmac_f32_e32 v128, 0x3f317217, v132
	v_fmac_f32_e32 v133, 0x3f317217, v137
	v_fmac_f32_e32 v128, 0x3377d1cf, v132
	v_fmac_f32_e32 v133, 0x3377d1cf, v137
	v_fmac_f32_e32 v128, 0x3f317217, v132
	v_fmac_f32_e32 v133, 0x3f317217, v137
	v_cndmask_b32_e32 v131, v131, v128, vcc
	v_cndmask_b32_e64 v136, v136, v133, s[24:25]
	v_add_f32_e32 v29, v29, v131
	v_add_f32_e32 v13, v13, v136
	global_store_dword v134, v29, s[0:1] offset:2304
	global_store_dword v134, v13, s[0:1] offset:2432
	v_add_f32_e32 v30, v30, v138
	v_add_f32_e32 v14, v14, v139
	v_mul_f32_e32 v128, 0xbfb8aa3b, v30
	v_mul_f32_e32 v133, 0xbfb8aa3b, v14
	v_exp_f32_e64 v128, -|v128|
	v_exp_f32_e64 v133, -|v133|
	v_max_f32_e32 v30, 0, v30
	v_max_f32_e32 v14, 0, v14
	v_fma_f32 v131, v128, s101, 0.5
	v_fma_f32 v136, v133, s101, 0.5
	v_cmp_le_f32_e32 vcc, s100, v128
	v_cmp_le_f32_e64 s[24:25], s100, v133
	v_fma_f32 v131, -v128, v131, 1.0
	v_fma_f32 v136, -v133, v136, 1.0
	v_add_f32_e32 v132, 1.0, v128
	v_add_f32_e32 v137, 1.0, v133
	v_mul_f32_e32 v131, v128, v131
	v_mul_f32_e32 v136, v133, v136
	v_log_f32_e32 v132, v132
	v_log_f32_e32 v137, v137
	v_mul_f32_e32 v128, 0xbf317217, v132
	v_mul_f32_e32 v133, 0xbf317217, v137
	v_fmac_f32_e32 v128, 0x3f317217, v132
	v_fmac_f32_e32 v133, 0x3f317217, v137
	v_fmac_f32_e32 v128, 0x3377d1cf, v132
	v_fmac_f32_e32 v133, 0x3377d1cf, v137
	v_fmac_f32_e32 v128, 0x3f317217, v132
	v_fmac_f32_e32 v133, 0x3f317217, v137
	v_cndmask_b32_e32 v131, v131, v128, vcc
	v_cndmask_b32_e64 v136, v136, v133, s[24:25]
	v_add_f32_e32 v30, v30, v131
	v_add_f32_e32 v14, v14, v136
	global_store_dword v134, v30, s[0:1] offset:2560
	global_store_dword v134, v14, s[0:1] offset:2688
	v_add_f32_e32 v31, v31, v138
	v_add_f32_e32 v15, v15, v139
	v_mul_f32_e32 v128, 0xbfb8aa3b, v31
	v_mul_f32_e32 v133, 0xbfb8aa3b, v15
	v_exp_f32_e64 v128, -|v128|
	v_exp_f32_e64 v133, -|v133|
	v_max_f32_e32 v31, 0, v31
	v_max_f32_e32 v15, 0, v15
	v_fma_f32 v131, v128, s101, 0.5
	v_fma_f32 v136, v133, s101, 0.5
	v_cmp_le_f32_e32 vcc, s100, v128
	v_cmp_le_f32_e64 s[24:25], s100, v133
	v_fma_f32 v131, -v128, v131, 1.0
	v_fma_f32 v136, -v133, v136, 1.0
	v_add_f32_e32 v132, 1.0, v128
	v_add_f32_e32 v137, 1.0, v133
	v_mul_f32_e32 v131, v128, v131
	v_mul_f32_e32 v136, v133, v136
	v_log_f32_e32 v132, v132
	v_log_f32_e32 v137, v137
	v_mul_f32_e32 v128, 0xbf317217, v132
	v_mul_f32_e32 v133, 0xbf317217, v137
	v_fmac_f32_e32 v128, 0x3f317217, v132
	v_fmac_f32_e32 v133, 0x3f317217, v137
	v_fmac_f32_e32 v128, 0x3377d1cf, v132
	v_fmac_f32_e32 v133, 0x3377d1cf, v137
	v_fmac_f32_e32 v128, 0x3f317217, v132
	v_fmac_f32_e32 v133, 0x3f317217, v137
	v_cndmask_b32_e32 v131, v131, v128, vcc
	v_cndmask_b32_e64 v136, v136, v133, s[24:25]
	v_add_f32_e32 v31, v31, v131
	v_add_f32_e32 v15, v15, v136
	global_store_dword v134, v31, s[0:1] offset:2816
	global_store_dword v134, v15, s[0:1] offset:2944

.LBB0_1978:
	s_ashr_i32 s6, s16, 3
	s_and_b32 s7, s16, 7
	s_lshl_b32 s17, s6, 7
	s_lshl_b32 s4, s7, 8
	v_readlane_b32 s12, v252, 45
	v_readlane_b32 s13, v252, 46
	s_add_u32 s12, s12, s4
	s_addc_u32 s13, s13, 0
	s_lshl_b32 s4, s17, 11
	s_add_u32 s12, s12, s4
	s_addc_u32 s13, s13, 0
	v_lshl_add_u32 v32, v234, 11, v72
	global_load_dwordx4 v[0:3], v32, s[12:13]
	s_add_u32 s12, s12, 0x8000
	s_addc_u32 s13, s13, 0
	global_load_dwordx4 v[4:7], v32, s[12:13]
	s_add_u32 s12, s12, 0x8000
	s_addc_u32 s13, s13, 0
	global_load_dwordx4 v[8:11], v32, s[12:13]
	s_add_u32 s12, s12, 0x8000
	s_addc_u32 s13, s13, 0
	global_load_dwordx4 v[12:15], v32, s[12:13]
	s_add_u32 s12, s12, 0x8000
	s_addc_u32 s13, s13, 0
	global_load_dwordx4 v[16:19], v32, s[12:13]
	s_add_u32 s12, s12, 0x8000
	s_addc_u32 s13, s13, 0
	global_load_dwordx4 v[20:23], v32, s[12:13]
	s_add_u32 s12, s12, 0x8000
	s_addc_u32 s13, s13, 0
	global_load_dwordx4 v[24:27], v32, s[12:13]
	s_add_u32 s12, s12, 0x8000
	s_addc_u32 s13, s13, 0
	global_load_dwordx4 v[28:31], v32, s[12:13]
	s_barrier
	s_waitcnt vmcnt(7)
	ds_write_b16 v235, v0
	ds_write_b16_d16_hi v235, v0 offset:272
	ds_write_b16 v235, v1 offset:544
	ds_write_b16_d16_hi v235, v1 offset:816
	ds_write_b16 v235, v2 offset:1088
	ds_write_b16_d16_hi v235, v2 offset:1360
	ds_write_b16 v235, v3 offset:1632
	ds_write_b16_d16_hi v235, v3 offset:1904
	s_waitcnt vmcnt(6)
	ds_write_b16 v235, v4 offset:32
	ds_write_b16_d16_hi v235, v4 offset:304
	ds_write_b16 v235, v5 offset:576
	ds_write_b16_d16_hi v235, v5 offset:848
	ds_write_b16 v235, v6 offset:1120
	ds_write_b16_d16_hi v235, v6 offset:1392
	ds_write_b16 v235, v7 offset:1664
	ds_write_b16_d16_hi v235, v7 offset:1936
	s_waitcnt vmcnt(5)
	ds_write_b16 v235, v8 offset:64
	ds_write_b16_d16_hi v235, v8 offset:336
	ds_write_b16 v235, v9 offset:608
	ds_write_b16_d16_hi v235, v9 offset:880
	ds_write_b16 v235, v10 offset:1152
	ds_write_b16_d16_hi v235, v10 offset:1424
	ds_write_b16 v235, v11 offset:1696
	ds_write_b16_d16_hi v235, v11 offset:1968
	s_waitcnt vmcnt(4)
	ds_write_b16 v235, v12 offset:96
	ds_write_b16_d16_hi v235, v12 offset:368
	ds_write_b16 v235, v13 offset:640
	ds_write_b16_d16_hi v235, v13 offset:912
	ds_write_b16 v235, v14 offset:1184
	ds_write_b16_d16_hi v235, v14 offset:1456
	ds_write_b16 v235, v15 offset:1728
	ds_write_b16_d16_hi v235, v15 offset:2000
	s_waitcnt vmcnt(3)
	ds_write_b16 v235, v16 offset:128
	ds_write_b16_d16_hi v235, v16 offset:400
	ds_write_b16 v235, v17 offset:672
	ds_write_b16_d16_hi v235, v17 offset:944
	ds_write_b16 v235, v18 offset:1216
	ds_write_b16_d16_hi v235, v18 offset:1488
	ds_write_b16 v235, v19 offset:1760
	ds_write_b16_d16_hi v235, v19 offset:2032
	s_waitcnt vmcnt(2)
	ds_write_b16 v235, v20 offset:160
	ds_write_b16_d16_hi v235, v20 offset:432
	ds_write_b16 v235, v21 offset:704
	ds_write_b16_d16_hi v235, v21 offset:976
	ds_write_b16 v235, v22 offset:1248
	ds_write_b16_d16_hi v235, v22 offset:1520
	ds_write_b16 v235, v23 offset:1792
	ds_write_b16_d16_hi v235, v23 offset:2064
	s_waitcnt vmcnt(1)
	ds_write_b16 v235, v24 offset:192
	ds_write_b16_d16_hi v235, v24 offset:464
	ds_write_b16 v235, v25 offset:736
	ds_write_b16_d16_hi v235, v25 offset:1008
	ds_write_b16 v235, v26 offset:1280
	ds_write_b16_d16_hi v235, v26 offset:1552
	ds_write_b16 v235, v27 offset:1824
	ds_write_b16_d16_hi v235, v27 offset:2096
	s_waitcnt vmcnt(0)
	ds_write_b16 v235, v28 offset:224
	ds_write_b16_d16_hi v235, v28 offset:496
	ds_write_b16 v235, v29 offset:768
	ds_write_b16_d16_hi v235, v29 offset:1040
	ds_write_b16 v235, v30 offset:1312
	ds_write_b16_d16_hi v235, v30 offset:1584
	ds_write_b16 v235, v31 offset:1856
	ds_write_b16_d16_hi v235, v31 offset:2128
	v_ashrrev_i32_e32 v0, 6, v65
	v_lshl_add_u32 v74, s7, 2, v0
	s_ashr_i32 s7, s6, 31
	v_lshlrev_b32_e32 v0, 6, v74
	s_lshl_b64 s[4:5], s[6:7], 11
	v_ashrrev_i32_e32 v1, 31, v0
	v_lshl_add_u64 v[0:1], s[4:5], 0, v[0:1]
	v_or_b32_e32 v0, v0, v64
	v_lshlrev_b64 v[0:1], 8, v[0:1]
	v_lshl_add_u64 v[0:1], v[66:67], 0, v[0:1]
	s_movk_i32 s11, 0x2000
	v_add_co_u32_e64 v2, s[4:5], s11, v0
	s_waitcnt lgkmcnt(0)
	s_nop 0
	v_addc_co_u32_e64 v3, s[4:5], 0, v1, s[4:5]
	s_barrier
	s_load_dwordx2 s[100:101], s[60:61], 0xe8
	v_readfirstlane_b32 s4, v74
	v_lshlrev_b32_e32 v84, 3, v221
	s_lshl_b32 s5, s6, 15
	s_waitcnt lgkmcnt(0)
	s_add_u32 s100, s100, s5
	s_addc_u32 s101, s101, 0
	s_lshl_b32 s4, s4, 9
	s_add_u32 s100, s100, s4
	s_addc_u32 s101, s101, 0
	s_add_u32 s100, s100, 0xd08000
	s_addc_u32 s101, s101, 0
	global_load_dwordx2 v[80:81], v84, s[100:101]
	s_add_u32 s100, s100, 0x4000
	s_addc_u32 s101, s101, 0
	global_load_dwordx2 v[82:83], v84, s[100:101]
	global_load_dwordx4 v[24:27], v[0:1], off
	global_load_dwordx4 v[28:31], v[0:1], off offset:32
	global_load_dwordx4 v[32:35], v[0:1], off offset:64
	global_load_dwordx4 v[36:39], v[0:1], off offset:96
	global_load_dwordx4 v[40:43], v[2:3], off
	global_load_dwordx4 v[44:47], v[2:3], off offset:32
	global_load_dwordx4 v[48:51], v[2:3], off offset:64
	global_load_dwordx4 v[52:55], v[2:3], off offset:96
	global_load_dwordx4 v[56:59], v[0:1], off offset:128
	global_load_dwordx4 v[60:63], v[2:3], off offset:128
	global_load_dwordx4 v[20:23], v[0:1], off offset:160
	global_load_dwordx4 v[12:15], v[0:1], off offset:192
	global_load_dwordx4 v[4:7], v[0:1], off offset:224
	global_load_dwordx4 v[16:19], v[2:3], off offset:160
	global_load_dwordx4 v[8:11], v[2:3], off offset:192
	s_nop 0
	global_load_dwordx4 v[0:3], v[2:3], off offset:224
	s_lshl_b64 s[4:5], s[6:7], 15
	s_lshl_b64 s[6:7], s[6:7], 6
	v_ashrrev_i32_e32 v75, 31, v74
	v_readlane_b32 s14, v252, 12
	s_mov_b32 s10, 0
	v_lshl_add_u64 v[76:77], v[68:69], 0, s[4:5]
	v_lshl_add_u64 v[78:79], s[6:7], 0, v[74:75]
	s_mov_b32 s6, 0
	s_movk_i32 s7, 0x3000
	s_movk_i32 s12, 0x1000
	v_readlane_b32 s15, v252, 13
	s_waitcnt vmcnt(16)
	ds_write_b64 v253, v[80:81]
	ds_write_b64 v253, v[82:83] offset:512
	s_waitcnt vmcnt(15)
	v_lshlrev_b32_e32 v80, 16, v24
	v_and_b32_e32 v81, 0xffff0000, v24
	v_lshlrev_b32_e32 v82, 16, v25
	v_and_b32_e32 v83, 0xffff0000, v25
	v_lshlrev_b32_e32 v84, 16, v26
	v_and_b32_e32 v85, 0xffff0000, v26
	v_lshlrev_b32_e32 v86, 16, v27
	v_and_b32_e32 v87, 0xffff0000, v27
	s_waitcnt vmcnt(14)
	v_lshlrev_b32_e32 v88, 16, v28
	v_and_b32_e32 v89, 0xffff0000, v28
	v_lshlrev_b32_e32 v90, 16, v29
	v_and_b32_e32 v91, 0xffff0000, v29
	v_lshlrev_b32_e32 v92, 16, v30
	v_and_b32_e32 v93, 0xffff0000, v30
	v_lshlrev_b32_e32 v94, 16, v31
	v_and_b32_e32 v95, 0xffff0000, v31
	s_waitcnt vmcnt(13)
	v_lshlrev_b32_e32 v96, 16, v32
	v_and_b32_e32 v97, 0xffff0000, v32
	v_lshlrev_b32_e32 v98, 16, v33
	v_and_b32_e32 v99, 0xffff0000, v33
	v_lshlrev_b32_e32 v100, 16, v34
	v_and_b32_e32 v101, 0xffff0000, v34
	v_lshlrev_b32_e32 v102, 16, v35
	v_and_b32_e32 v103, 0xffff0000, v35
	s_waitcnt vmcnt(12)
	v_lshlrev_b32_e32 v104, 16, v36
	v_and_b32_e32 v105, 0xffff0000, v36
	v_lshlrev_b32_e32 v106, 16, v37
	s_waitcnt vmcnt(11)
	v_lshlrev_b32_e32 v108, 16, v40
	v_and_b32_e32 v109, 0xffff0000, v40
	v_lshlrev_b32_e32 v110, 16, v41
	v_and_b32_e32 v111, 0xffff0000, v41
	v_lshlrev_b32_e32 v112, 16, v42
	v_and_b32_e32 v113, 0xffff0000, v42
	v_lshlrev_b32_e32 v114, 16, v43
	v_and_b32_e32 v115, 0xffff0000, v43
	s_waitcnt vmcnt(10)
	v_lshlrev_b32_e32 v116, 16, v44
	v_and_b32_e32 v117, 0xffff0000, v44
	v_lshlrev_b32_e32 v118, 16, v45
	v_and_b32_e32 v119, 0xffff0000, v45
	v_lshlrev_b32_e32 v120, 16, v46
	v_and_b32_e32 v121, 0xffff0000, v46
	v_lshlrev_b32_e32 v122, 16, v47
	v_and_b32_e32 v123, 0xffff0000, v47
	s_waitcnt vmcnt(9)
	v_lshlrev_b32_e32 v124, 16, v48
	v_and_b32_e32 v125, 0xffff0000, v48
	v_lshlrev_b32_e32 v126, 16, v49
	v_and_b32_e32 v127, 0xffff0000, v49
	v_lshlrev_b32_e32 v130, 16, v50
	v_and_b32_e32 v131, 0xffff0000, v50
	v_lshlrev_b32_e32 v132, 16, v51
	v_and_b32_e32 v133, 0xffff0000, v51
	v_and_b32_e32 v107, 0xffff0000, v37
	v_lshlrev_b32_e32 v134, 16, v38
	v_and_b32_e32 v135, 0xffff0000, v38
	v_lshlrev_b32_e32 v136, 16, v39
	v_and_b32_e32 v137, 0xffff0000, v39
	s_waitcnt vmcnt(8)
	v_lshlrev_b32_e32 v138, 16, v52
	v_and_b32_e32 v139, 0xffff0000, v52
	v_lshlrev_b32_e32 v140, 16, v53
	v_and_b32_e32 v141, 0xffff0000, v53
	v_lshlrev_b32_e32 v142, 16, v54
	v_and_b32_e32 v143, 0xffff0000, v54
	v_lshlrev_b32_e32 v144, 16, v55
	v_and_b32_e32 v145, 0xffff0000, v55
	s_waitcnt vmcnt(7)
	v_lshlrev_b32_e32 v146, 16, v56
	v_and_b32_e32 v147, 0xffff0000, v56
	v_lshlrev_b32_e32 v148, 16, v57
	v_and_b32_e32 v149, 0xffff0000, v57
	v_lshlrev_b32_e32 v150, 16, v58
	v_and_b32_e32 v151, 0xffff0000, v58
	v_lshlrev_b32_e32 v152, 16, v59
	v_and_b32_e32 v153, 0xffff0000, v59
	s_waitcnt vmcnt(6)
	v_lshlrev_b32_e32 v154, 16, v60
	v_and_b32_e32 v155, 0xffff0000, v60
	v_lshlrev_b32_e32 v156, 16, v61
	v_and_b32_e32 v157, 0xffff0000, v61
	v_lshlrev_b32_e32 v158, 16, v62
	v_and_b32_e32 v159, 0xffff0000, v62
	v_lshlrev_b32_e32 v160, 16, v63
	v_and_b32_e32 v161, 0xffff0000, v63
	s_waitcnt vmcnt(5)
	v_lshlrev_b32_e32 v168, 16, v20
	v_and_b32_e32 v169, 0xffff0000, v20
	v_lshlrev_b32_e32 v170, 16, v21
	v_and_b32_e32 v171, 0xffff0000, v21
	v_lshlrev_b32_e32 v172, 16, v22
	v_and_b32_e32 v173, 0xffff0000, v22
	v_lshlrev_b32_e32 v174, 16, v23
	v_and_b32_e32 v175, 0xffff0000, v23
	s_waitcnt vmcnt(2)
	v_lshlrev_b32_e32 v176, 16, v16
	v_and_b32_e32 v177, 0xffff0000, v16
	v_lshlrev_b32_e32 v178, 16, v17
	v_and_b32_e32 v179, 0xffff0000, v17
	v_lshlrev_b32_e32 v180, 16, v18
	v_and_b32_e32 v181, 0xffff0000, v18
	v_lshlrev_b32_e32 v182, 16, v19
	v_and_b32_e32 v183, 0xffff0000, v19
	v_lshlrev_b32_e32 v184, 16, v12
	v_and_b32_e32 v185, 0xffff0000, v12
	v_lshlrev_b32_e32 v186, 16, v13
	v_and_b32_e32 v187, 0xffff0000, v13
	v_lshlrev_b32_e32 v188, 16, v14
	v_and_b32_e32 v189, 0xffff0000, v14
	v_lshlrev_b32_e32 v190, 16, v15
	v_and_b32_e32 v191, 0xffff0000, v15
	s_waitcnt vmcnt(1)
	v_lshlrev_b32_e32 v192, 16, v8
	v_and_b32_e32 v193, 0xffff0000, v8
	v_lshlrev_b32_e32 v194, 16, v9
	v_and_b32_e32 v195, 0xffff0000, v9
	v_lshlrev_b32_e32 v196, 16, v10
	v_and_b32_e32 v197, 0xffff0000, v10
	v_lshlrev_b32_e32 v198, 16, v11
	v_and_b32_e32 v199, 0xffff0000, v11
	v_lshlrev_b32_e32 v200, 16, v4
	v_and_b32_e32 v201, 0xffff0000, v4
	v_lshlrev_b32_e32 v202, 16, v5
	v_and_b32_e32 v203, 0xffff0000, v5
	v_lshlrev_b32_e32 v204, 16, v6
	v_and_b32_e32 v205, 0xffff0000, v6
	v_lshlrev_b32_e32 v206, 16, v7
	v_and_b32_e32 v207, 0xffff0000, v7
	s_waitcnt vmcnt(0)
	v_lshlrev_b32_e32 v208, 16, v0
	v_and_b32_e32 v209, 0xffff0000, v0
	v_lshlrev_b32_e32 v210, 16, v1
	v_and_b32_e32 v211, 0xffff0000, v1
	v_lshlrev_b32_e32 v212, 16, v2
	v_and_b32_e32 v213, 0xffff0000, v2
	v_lshlrev_b32_e32 v214, 16, v3
	v_and_b32_e32 v215, 0xffff0000, v3

.LBB0_2103:
	v_writelane_b32 v255, s19, 57
	s_nop 0
	v_readlane_b32 s14, v255, 50
	s_add_i32 s22, s19, s14
	s_lshl_b32 s14, s22, 14
	v_readlane_b32 s15, v255, 51
	s_add_u32 s14, s15, s14
	v_readlane_b32 s15, v255, 54
	s_addc_u32 s15, s15, 0
	s_lshl_b64 s[16:17], s[22:23], 14
	v_readlane_b32 s19, v255, 55
	s_add_u32 s16, s19, s16
	v_readlane_b32 s19, v255, 56
	s_addc_u32 s17, s19, s17
	s_lshl_b64 s[20:21], s[22:23], 13
	v_readlane_b32 vcc_lo, v255, 52
	v_readlane_b32 vcc_hi, v255, 53
	s_add_u32 s20, s20, vcc_lo
	s_addc_u32 s21, s21, vcc_hi
	s_lshl_b64 s[20:21], s[20:21], 1
	s_or_b32 s19, s20, 0x80000
	v_readlane_b32 vcc_lo, v252, 49
	v_readlane_b32 vcc_hi, v252, 50
	s_add_u32 s20, vcc_lo, s19
	v_lshl_add_u64 v[64:65], s[14:15], 0, v[176:177]
	s_addc_u32 s21, vcc_hi, s21
	s_lshl_b32 s100, s22, 7
	s_add_u32 s100, s100, s12
	s_lshl_b32 s100, s100, 2
	s_mov_b32 s101, 0
	v_lshl_add_u64 v[222:223], s[100:101], 0, v[216:217]
	global_load_dwordx2 v[224:225], v[222:223], off
	global_load_dwordx4 v[64:67], v[64:65], off
	v_lshl_add_u64 v[68:69], s[16:17], 0, v[176:177]
	global_load_dwordx4 v[68:71], v[68:69], off
	v_lshl_add_u64 v[72:73], s[20:21], 0, v[176:177]
	global_load_dwordx4 v[72:75], v[72:73], off
	v_lshl_add_u64 v[76:77], s[14:15], 0, v[178:179]
	global_load_dwordx4 v[76:79], v[76:77], off
	v_lshl_add_u64 v[80:81], s[16:17], 0, v[178:179]
	global_load_dwordx4 v[80:83], v[80:81], off
	v_lshl_add_u64 v[84:85], s[20:21], 0, v[178:179]
	global_load_dwordx4 v[84:87], v[84:85], off
	v_lshl_add_u64 v[88:89], s[14:15], 0, v[180:181]
	global_load_dwordx4 v[88:91], v[88:89], off
	v_lshl_add_u64 v[92:93], s[16:17], 0, v[180:181]
	global_load_dwordx4 v[92:95], v[92:93], off
	v_lshl_add_u64 v[96:97], s[20:21], 0, v[180:181]
	global_load_dwordx4 v[96:99], v[96:97], off
	v_lshl_add_u64 v[100:101], s[14:15], 0, v[182:183]
	global_load_dwordx4 v[100:103], v[100:101], off
	v_lshl_add_u64 v[104:105], s[16:17], 0, v[182:183]
	global_load_dwordx4 v[104:107], v[104:105], off
	v_lshl_add_u64 v[108:109], s[20:21], 0, v[182:183]
	global_load_dwordx4 v[108:111], v[108:109], off
	v_writelane_b32 v252, s22, 12
	s_lshl_b32 s19, s22, 7
	s_mov_b64 s[14:15], -1
	v_writelane_b32 v252, s23, 13
	s_mov_b32 s20, 0
	s_barrier
	s_waitcnt vmcnt(11)
	ds_write_b64 v226, v[224:225]
	ds_write_b128 v201, v[64:67]
	s_waitcnt vmcnt(10)
	ds_write_b128 v201, v[68:71] offset:17408
	s_waitcnt vmcnt(9)
	ds_write_b128 v201, v[72:75] offset:34816
	s_waitcnt vmcnt(8)
	ds_write_b128 v202, v[76:79]
	s_waitcnt vmcnt(7)
	ds_write_b128 v202, v[80:83] offset:17408
	s_waitcnt vmcnt(6)
	ds_write_b128 v202, v[84:87] offset:34816
	s_waitcnt vmcnt(5)
	ds_write_b128 v203, v[88:91]
	s_waitcnt vmcnt(4)
	ds_write_b128 v203, v[92:95] offset:17408
	s_waitcnt vmcnt(3)
	ds_write_b128 v203, v[96:99] offset:34816
	s_waitcnt vmcnt(2)
	ds_write_b128 v204, v[100:103]
	s_waitcnt vmcnt(1)
	ds_write_b128 v204, v[104:107] offset:17408
	s_waitcnt vmcnt(0)
	ds_write_b128 v204, v[108:111] offset:34816
	v_mov_b32_e32 v78, v129
	v_mov_b32_e32 v79, v129
	v_mov_b32_e32 v64, v129
	v_mov_b32_e32 v65, v129
	v_mov_b32_e32 v66, v129
	v_mov_b32_e32 v67, v129
	v_mov_b32_e32 v68, v129
	v_mov_b32_e32 v69, v129
	v_mov_b32_e32 v70, v129
	v_mov_b32_e32 v71, v129
	v_mov_b32_e32 v72, v129
	v_mov_b32_e32 v73, v129
	v_mov_b32_e32 v74, v129
	v_mov_b32_e32 v75, v129
	v_mov_b32_e32 v76, v129
	v_mov_b32_e32 v77, v129
	v_mov_b64_e32 v[94:95], v[78:79]
	v_mov_b64_e32 v[92:93], v[76:77]
	v_mov_b64_e32 v[90:91], v[74:75]
	v_mov_b64_e32 v[88:89], v[72:73]
	v_mov_b64_e32 v[86:87], v[70:71]
	v_mov_b64_e32 v[84:85], v[68:69]
	v_mov_b64_e32 v[82:83], v[66:67]
	v_mov_b64_e32 v[80:81], v[64:65]
	s_waitcnt lgkmcnt(0)
	s_barrier
	s_branch .LBB0_2105
